# final phase: hand-written row loop, norm weights loaded once per block, out_proj and x chunks of both rows requested up front (32 loads in flight) instead of one store+load round trip per column step;
# speedup vs baseline: 1.0139x; 1.0065x over previous
.Lpg_hb_done:
	s_or_b64 exec, exec, s[6:7]
	v_ashrrev_i32_e32 v41, 31, v40
	v_lshlrev_b64 v[36:37], 13, v[40:41]
	v_lshlrev_b32_e32 v20, 1, v0
	v_lshl_or_b32 v22, v105, 6, v36
	v_lshl_add_u64 v[2:3], s[68:69], 0, v[20:21]
	v_mad_u64_u32 v[2:3], s[4:5], v22, s29, v[2:3]
	v_mad_i32_i24 v3, v37, s29, v3
	v_add_co_u32_e32 v6, vcc, s29, v2
	global_load_ushort v84, v[2:3], off
	s_nop 0
	v_addc_co_u32_e32 v7, vcc, 0, v3, vcc
	global_load_ushort v85, v[6:7], off
	v_add_co_u32_e32 v6, vcc, s30, v2
	s_mov_b32 s2, 0x12000
	s_nop 0
	v_addc_co_u32_e32 v7, vcc, 0, v3, vcc
	global_load_ushort v99, v[6:7], off
	v_add_co_u32_e32 v6, vcc, s2, v2
	s_mov_b32 s2, 0x18000
	s_nop 0
	v_addc_co_u32_e32 v7, vcc, 0, v3, vcc
	global_load_ushort v104, v[6:7], off
	v_add_co_u32_e32 v6, vcc, s2, v2
	s_mov_b32 s2, 0x84000
	s_nop 0
	v_addc_co_u32_e32 v7, vcc, 0, v3, vcc
	global_load_ushort v91, v[6:7], off
	v_add_co_u32_e32 v6, vcc, s35, v2
	v_readlane_b32 s36, v250, 3
	s_nop 0
	v_addc_co_u32_e32 v7, vcc, 0, v3, vcc
	global_load_ushort v101, v[6:7], off
	v_add_co_u32_e32 v6, vcc, s60, v2
	v_mov_b32_e32 v1, v21
	s_nop 0
	v_addc_co_u32_e32 v7, vcc, 0, v3, vcc
	global_load_ushort v88, v[6:7], off
	v_add_co_u32_e32 v6, vcc, s61, v2
	v_readlane_b32 s48, v250, 15
	s_nop 0
	v_addc_co_u32_e32 v7, vcc, 0, v3, vcc
	global_load_ushort v93, v[6:7], off
	v_add_co_u32_e32 v6, vcc, s66, v2
	v_readlane_b32 s49, v250, 16
	s_nop 0
	v_addc_co_u32_e32 v7, vcc, 0, v3, vcc
	global_load_ushort v96, v[6:7], off
	v_add_co_u32_e32 v6, vcc, s67, v2
	v_lshl_add_u64 v[0:1], v[0:1], 2, s[48:49]
	s_nop 0
	v_addc_co_u32_e32 v7, vcc, 0, v3, vcc
	global_load_ushort v97, v[6:7], off
	v_add_co_u32_e32 v6, vcc, s64, v2
	v_lshlrev_b32_e32 v20, 2, v5
	s_nop 0
	v_addc_co_u32_e32 v7, vcc, 0, v3, vcc
	global_load_ushort v83, v[6:7], off
	v_add_co_u32_e32 v6, vcc, s65, v2
	global_load_dword v28, v[0:1], off
	s_nop 0
	v_addc_co_u32_e32 v7, vcc, 0, v3, vcc
	global_load_ushort v89, v[6:7], off
	v_add_co_u32_e32 v6, vcc, s74, v2
	v_lshl_add_u64 v[0:1], s[48:49], 0, v[20:21]
	s_nop 0
	v_addc_co_u32_e32 v7, vcc, 0, v3, vcc
	global_load_ushort v78, v[6:7], off
	v_add_co_u32_e32 v6, vcc, s75, v2
	v_lshlrev_b32_e32 v27, 7, v4
	s_nop 0
	v_addc_co_u32_e32 v7, vcc, 0, v3, vcc
	global_load_ushort v81, v[6:7], off
	v_add_co_u32_e32 v6, vcc, s59, v2
	v_readlane_b32 s37, v250, 4
	s_nop 0
	v_addc_co_u32_e32 v7, vcc, 0, v3, vcc
	global_load_ushort v70, v[6:7], off
	v_add_co_u32_e32 v6, vcc, s22, v2
	v_readlane_b32 s38, v250, 5
	s_nop 0
	v_addc_co_u32_e32 v7, vcc, 0, v3, vcc
	global_load_ushort v73, v[6:7], off
	v_add_co_u32_e32 v6, vcc, s23, v2
	v_readlane_b32 s39, v250, 6
	s_nop 0
	v_addc_co_u32_e32 v7, vcc, 0, v3, vcc
	global_load_ushort v75, v[6:7], off
	v_add_co_u32_e32 v6, vcc, s12, v2
	v_readlane_b32 s40, v250, 7
	s_nop 0
	v_addc_co_u32_e32 v7, vcc, 0, v3, vcc
	global_load_ushort v79, v[6:7], off
	v_add_co_u32_e32 v6, vcc, s13, v2
	v_readlane_b32 s41, v250, 8
	s_nop 0
	v_addc_co_u32_e32 v7, vcc, 0, v3, vcc
	global_load_ushort v67, v[6:7], off
	v_add_co_u32_e32 v6, vcc, s28, v2
	v_readlane_b32 s42, v250, 9
	s_nop 0
	v_addc_co_u32_e32 v7, vcc, 0, v3, vcc
	global_load_ushort v71, v[6:7], off
	v_add_co_u32_e32 v6, vcc, s52, v2
	v_readlane_b32 s43, v250, 10
	s_nop 0
	v_addc_co_u32_e32 v7, vcc, 0, v3, vcc
	global_load_ushort v50, v[6:7], off
	v_add_co_u32_e32 v6, vcc, s53, v2
	v_readlane_b32 s44, v250, 11
	s_nop 0
	v_addc_co_u32_e32 v7, vcc, 0, v3, vcc
	global_load_ushort v65, v[6:7], off
	v_add_co_u32_e32 v6, vcc, s2, v2
	s_mov_b32 s2, 0x8a000
	s_nop 0
	v_addc_co_u32_e32 v7, vcc, 0, v3, vcc
	global_load_ushort v41, v[6:7], off
	v_add_co_u32_e32 v6, vcc, s2, v2
	s_mov_b32 s2, 0x90000
	s_nop 0
	v_addc_co_u32_e32 v7, vcc, 0, v3, vcc
	global_load_ushort v51, v[6:7], off
	v_add_co_u32_e32 v6, vcc, s2, v2
	s_mov_b32 s2, 0x96000
	s_nop 0
	v_addc_co_u32_e32 v7, vcc, 0, v3, vcc
	global_load_ushort v59, v[6:7], off
	v_add_co_u32_e32 v6, vcc, s2, v2
	s_mov_b32 s2, 0x9c000
	s_nop 0
	v_addc_co_u32_e32 v7, vcc, 0, v3, vcc
	global_load_ushort v63, v[6:7], off
	v_add_co_u32_e32 v6, vcc, s2, v2
	s_mov_b32 s2, 0xa2000
	s_nop 0
	v_addc_co_u32_e32 v7, vcc, 0, v3, vcc
	global_load_ushort v55, v[6:7], off
	v_add_co_u32_e32 v6, vcc, s2, v2
	s_mov_b32 s2, 0xa8000
	s_nop 0
	v_addc_co_u32_e32 v7, vcc, 0, v3, vcc
	global_load_ushort v58, v[6:7], off
	v_add_co_u32_e32 v6, vcc, s2, v2
	s_mov_b32 s2, 0xae000
	s_nop 0
	v_addc_co_u32_e32 v7, vcc, 0, v3, vcc
	global_load_ushort v53, v[6:7], off
	v_add_co_u32_e32 v6, vcc, s2, v2
	s_mov_b32 s2, 0xb4000
	s_nop 0
	v_addc_co_u32_e32 v7, vcc, 0, v3, vcc
	global_load_ushort v57, v[6:7], off
	v_add_co_u32_e32 v6, vcc, s2, v2
	s_mov_b32 s2, 0xba000
	s_nop 0
	v_addc_co_u32_e32 v7, vcc, 0, v3, vcc
	global_load_ushort v52, v[6:7], off
	v_add_co_u32_e32 v6, vcc, s2, v2
	s_mov_b32 s2, 0xc0000
	s_nop 0
	v_addc_co_u32_e32 v7, vcc, 0, v3, vcc
	global_load_ushort v54, v[6:7], off
	v_add_co_u32_e32 v6, vcc, s2, v2
	s_mov_b32 s2, 0xc6000
	s_nop 0
	v_addc_co_u32_e32 v7, vcc, 0, v3, vcc
	global_load_ushort v56, v[6:7], off
	v_add_co_u32_e32 v6, vcc, s2, v2
	s_mov_b32 s2, 0xcc000
	s_nop 0
	v_addc_co_u32_e32 v7, vcc, 0, v3, vcc
	global_load_ushort v62, v[6:7], off
	v_add_co_u32_e32 v6, vcc, s2, v2
	s_mov_b32 s2, 0xd2000
	s_nop 0
	v_addc_co_u32_e32 v7, vcc, 0, v3, vcc
	global_load_ushort v60, v[6:7], off
	v_add_co_u32_e32 v6, vcc, s2, v2
	s_mov_b32 s2, 0xd8000
	s_nop 0
	v_addc_co_u32_e32 v7, vcc, 0, v3, vcc
	global_load_ushort v61, v[6:7], off
	v_add_co_u32_e32 v6, vcc, s2, v2
	s_mov_b32 s2, 0xde000
	s_nop 0
	v_addc_co_u32_e32 v7, vcc, 0, v3, vcc
	global_load_ushort v64, v[6:7], off
	v_add_co_u32_e32 v6, vcc, s2, v2
	s_mov_b32 s2, 0xe4000
	s_nop 0
	v_addc_co_u32_e32 v7, vcc, 0, v3, vcc
	global_load_ushort v66, v[6:7], off
	v_add_co_u32_e32 v6, vcc, s2, v2
	s_mov_b32 s2, 0xea000
	s_nop 0
	v_addc_co_u32_e32 v7, vcc, 0, v3, vcc
	global_load_ushort v68, v[6:7], off
	v_add_co_u32_e32 v6, vcc, s2, v2
	s_mov_b32 s2, 0xf0000
	s_nop 0
	v_addc_co_u32_e32 v7, vcc, 0, v3, vcc
	global_load_ushort v69, v[6:7], off
	v_add_co_u32_e32 v6, vcc, s2, v2
	s_mov_b32 s2, 0xf6000
	s_nop 0
	v_addc_co_u32_e32 v7, vcc, 0, v3, vcc
	global_load_ushort v72, v[6:7], off
	v_add_co_u32_e32 v6, vcc, s2, v2
	s_mov_b32 s2, 0xfc000
	s_nop 0
	v_addc_co_u32_e32 v7, vcc, 0, v3, vcc
	global_load_ushort v74, v[6:7], off
	v_add_co_u32_e32 v6, vcc, s2, v2
	s_mov_b32 s2, 0x102000
	s_nop 0
	v_addc_co_u32_e32 v7, vcc, 0, v3, vcc
	global_load_ushort v76, v[6:7], off
	v_add_co_u32_e32 v6, vcc, s2, v2
	s_mov_b32 s2, 0x108000
	s_nop 0
	v_addc_co_u32_e32 v7, vcc, 0, v3, vcc
	global_load_ushort v77, v[6:7], off
	v_add_co_u32_e32 v6, vcc, s2, v2
	s_mov_b32 s2, 0x10e000
	s_nop 0
	v_addc_co_u32_e32 v7, vcc, 0, v3, vcc
	global_load_ushort v80, v[6:7], off
	v_add_co_u32_e32 v6, vcc, s2, v2
	s_mov_b32 s2, 0x114000
	s_nop 0
	v_addc_co_u32_e32 v7, vcc, 0, v3, vcc
	global_load_ushort v82, v[6:7], off
	v_add_co_u32_e32 v6, vcc, s2, v2
	s_mov_b32 s2, 0x11a000
	s_nop 0
	v_addc_co_u32_e32 v7, vcc, 0, v3, vcc
	global_load_ushort v86, v[6:7], off
	v_add_co_u32_e32 v6, vcc, s2, v2
	s_mov_b32 s2, 0x120000
	s_nop 0
	v_addc_co_u32_e32 v7, vcc, 0, v3, vcc
	global_load_ushort v87, v[6:7], off
	v_add_co_u32_e32 v6, vcc, s2, v2
	s_mov_b32 s2, 0x126000
	s_nop 0
	v_addc_co_u32_e32 v7, vcc, 0, v3, vcc
	global_load_ushort v90, v[6:7], off
	v_add_co_u32_e32 v6, vcc, s2, v2
	s_mov_b32 s2, 0x12c000
	s_nop 0
	v_addc_co_u32_e32 v7, vcc, 0, v3, vcc
	global_load_ushort v92, v[6:7], off
	v_add_co_u32_e32 v6, vcc, s2, v2
	s_mov_b32 s2, 0x132000
	s_nop 0
	v_addc_co_u32_e32 v7, vcc, 0, v3, vcc
	global_load_ushort v94, v[6:7], off
	v_add_co_u32_e32 v6, vcc, s2, v2
	s_mov_b32 s2, 0x138000
	s_nop 0
	v_addc_co_u32_e32 v7, vcc, 0, v3, vcc
	global_load_ushort v95, v[6:7], off
	v_add_co_u32_e32 v6, vcc, s2, v2
	s_mov_b32 s2, 0x13e000
	s_nop 0
	v_addc_co_u32_e32 v7, vcc, 0, v3, vcc
	global_load_ushort v98, v[6:7], off
	v_add_co_u32_e32 v6, vcc, s2, v2
	s_mov_b32 s2, 0x144000
	s_nop 0
	v_addc_co_u32_e32 v7, vcc, 0, v3, vcc
	global_load_ushort v100, v[6:7], off
	v_add_co_u32_e32 v6, vcc, s2, v2
	s_mov_b32 s2, 0x14a000
	s_nop 0
	v_addc_co_u32_e32 v7, vcc, 0, v3, vcc
	global_load_ushort v102, v[6:7], off
	v_add_co_u32_e32 v6, vcc, s2, v2
	s_mov_b32 s2, 0x150000
	s_nop 0
	v_addc_co_u32_e32 v7, vcc, 0, v3, vcc
	global_load_ushort v103, v[6:7], off
	v_add_co_u32_e32 v6, vcc, s2, v2
	s_mov_b32 s2, 0x156000
	s_nop 0
	v_addc_co_u32_e32 v7, vcc, 0, v3, vcc
	global_load_ushort v106, v[6:7], off
	v_add_co_u32_e32 v6, vcc, s2, v2
	s_mov_b32 s2, 0x15c000
	s_nop 0
	v_addc_co_u32_e32 v7, vcc, 0, v3, vcc
	global_load_ushort v116, v[6:7], off
	v_add_co_u32_e32 v6, vcc, s2, v2
	s_mov_b32 s2, 0x162000
	s_nop 0
	v_addc_co_u32_e32 v7, vcc, 0, v3, vcc
	global_load_ushort v142, v[6:7], off
	v_add_co_u32_e32 v6, vcc, s2, v2
	s_mov_b32 s2, 0x168000
	s_nop 0
	v_addc_co_u32_e32 v7, vcc, 0, v3, vcc
	global_load_ushort v143, v[6:7], off
	v_add_co_u32_e32 v6, vcc, s2, v2
	s_mov_b32 s2, 0x16e000
	s_nop 0
	v_addc_co_u32_e32 v7, vcc, 0, v3, vcc
	global_load_ushort v138, v[6:7], off
	v_add_co_u32_e32 v6, vcc, s2, v2
	s_mov_b32 s2, 0x174000
	s_nop 0
	v_addc_co_u32_e32 v7, vcc, 0, v3, vcc
	global_load_ushort v139, v[6:7], off
	v_add_co_u32_e32 v6, vcc, s2, v2
	s_mov_b32 s2, 0x17a000
	s_nop 0
	v_addc_co_u32_e32 v7, vcc, 0, v3, vcc
	v_add_co_u32_e32 v2, vcc, s2, v2
	global_load_ushort v137, v[6:7], off
	s_nop 0
	v_addc_co_u32_e32 v3, vcc, 0, v3, vcc
	global_load_ushort v207, v[2:3], off
	v_add_co_u32_e32 v2, vcc, s30, v0
	s_movk_i32 s2, 0x400
	s_nop 0
	v_addc_co_u32_e32 v3, vcc, 0, v1, vcc
	global_load_dword v29, v[2:3], off
	v_add_co_u32_e32 v2, vcc, 0x14000, v0
	v_readlane_b32 s45, v250, 12
	s_nop 0
	v_addc_co_u32_e32 v3, vcc, 0, v1, vcc
	v_add_co_u32_e32 v0, vcc, 0x1c000, v0
	global_load_dword v30, v[2:3], off
	s_nop 0
	v_addc_co_u32_e32 v1, vcc, 0, v1, vcc
	global_load_dword v31, v[0:1], off
	v_cmp_gt_i32_e32 vcc, s2, v38
	v_readlane_b32 s46, v250, 13
	v_readlane_b32 s47, v250, 14
	v_readlane_b32 s50, v250, 17
	v_readlane_b32 s51, v250, 18
	s_waitcnt vmcnt(63) expcnt(7) lgkmcnt(15)
	s_barrier
	s_waitcnt vmcnt(63)
	v_lshlrev_b32_e32 v251, 2, v38
	ds_write_b32 v251, v252
	ds_write_b32 v251, v253 offset:2048
	v_readlane_b32 s36, v250, 3
	v_readlane_b32 s37, v250, 4
	v_readlane_b32 s38, v250, 5
	v_readlane_b32 s39, v250, 6
	v_readlane_b32 s40, v250, 7
	v_readlane_b32 s41, v250, 8
	v_readlane_b32 s42, v250, 9
	v_readlane_b32 s43, v250, 10
	v_readlane_b32 s44, v250, 11
	v_readlane_b32 s45, v250, 12
	v_readlane_b32 s46, v250, 13
	v_readlane_b32 s47, v250, 14
	v_readlane_b32 s48, v250, 15
	v_readlane_b32 s49, v250, 16
	v_readlane_b32 s50, v250, 17
	v_readlane_b32 s51, v250, 18
	v_sub_u32_e64 v0, v105, 1 clamp
	v_and_b32_e32 v194, 0xff, v38
	v_or_b32_e32 v12, v0, v8
	v_lshlrev_b32_e32 v39, 6, v105
	v_mad_i64_i32 v[16:17], s[4:5], v12, 3, 0
	v_lshrrev_b32_e32 v24, 4, v194
	v_or_b32_e32 v36, v36, v39
	v_cmp_lt_u32_e32 vcc, 47, v194
	v_mov_b64_e32 v[4:5], 0x20600000
	v_mov_b64_e32 v[2:3], 0x5000
	v_add_u32_e32 v18, -3, v24
	v_mov_b32_e32 v6, v24
	v_mov_b64_e32 v[8:9], v[16:17]
	s_waitcnt lgkmcnt(0)
	s_barrier
	s_and_saveexec_b64 s[4:5], vcc
	v_mov_b64_e32 v[4:5], 0x8100000
	v_mov_b64_e32 v[2:3], 0x6000
	v_mov_b32_e32 v6, v18
	v_mov_b64_e32 v[8:9], v[36:37]
	s_or_b64 exec, exec, s[4:5]
	v_lshlrev_b32_e32 v195, 3, v38
	v_and_b32_e32 v25, 0x78, v195
	v_or_b32_e32 v113, v27, v25
	v_lshlrev_b32_e32 v20, 1, v113
	v_lshl_add_u64 v[4:5], s[82:83], 0, v[4:5]
	v_mov_b32_e32 v7, v21
	v_lshl_add_u64 v[4:5], v[4:5], 0, v[20:21]
	v_lshl_add_u64 v[6:7], v[8:9], 0, v[6:7]
	v_mad_u64_u32 v[4:5], s[4:5], v6, v2, v[4:5]
	v_mov_b32_e32 v6, v5
	v_mad_u64_u32 v[2:3], s[4:5], v7, v2, v[6:7]
	v_cmp_lt_u32_e64 s[4:5], 31, v194
	v_lshl_add_u64 v[0:1], s[14:15], 0, v[20:21]
	v_lshl_add_u64 v[48:49], s[68:69], 0, v[20:21]
	v_cndmask_b32_e64 v10, 1, -2, s[4:5]
	v_mov_b32_e32 v5, v2
	v_cndmask_b32_e64 v3, v17, v37, s[4:5]
	v_cndmask_b32_e64 v2, v16, v36, s[4:5]
	v_add_u32_e32 v20, v10, v24
	v_cndmask_b32_e64 v114, v189, v190, s[4:5]
	v_cndmask_b32_e64 v9, v1, v49, s[4:5]
	v_cndmask_b32_e64 v8, v0, v48, s[4:5]
	v_lshl_add_u64 v[46:47], v[2:3], 0, v[20:21]
	v_mul_lo_u32 v20, v47, v114
	v_mad_u64_u32 v[2:3], s[6:7], v46, v114, v[8:9]
	v_add_u32_e32 v3, v20, v3
	global_load_dwordx4 v[4:7], v[4:5], off
	v_cmp_lt_u32_e64 s[6:7], 15, v194
	global_load_dwordx4 v[8:11], v[2:3], off
	v_add_u32_e32 v42, -1, v24
	s_and_saveexec_b64 s[8:9], s[6:7]
	s_xor_b64 s[8:9], exec, s[8:9]
	v_mov_b32_e32 v43, v21
	v_lshl_add_u64 v[0:1], v[36:37], 0, v[42:43]
	v_mad_u64_u32 v[2:3], s[10:11], v0, s29, v[48:49]
	v_mov_b32_e32 v0, v3
	v_mad_u64_u32 v[0:1], s[10:11], v1, s29, v[0:1]
	v_mov_b32_e32 v3, v0
	s_or_saveexec_b64 s[8:9], s[8:9]
	s_mov_b32 s2, 0xf000
	v_mad_i64_i32 v[44:45], s[10:11], v12, s2, 0
	s_xor_b64 exec, exec, s[8:9]
	v_lshl_add_u64 v[0:1], v[0:1], 0, v[44:45]
	s_mov_b64 s[10:11], 0xa000
	v_lshl_add_u64 v[2:3], v[0:1], 0, s[10:11]
	s_or_b64 exec, exec, s[8:9]
	v_or_b32_e32 v115, v36, v24
	global_load_dwordx4 v[12:15], v[2:3], off
	v_mul_lo_u32 v112, v37, s29
	v_mad_u64_u32 v[0:1], s[8:9], v115, s29, v[48:49]
	v_add_u32_e32 v1, v112, v1
	global_load_dwordx4 v[0:3], v[0:1], off
	v_or_b32_e32 v244, 0x100, v194
	v_lshrrev_b32_e32 v245, 4, v244
	v_add_u32_e32 v208, -3, v245
	v_add_u32_e32 v210, -2, v245
	v_or_b32_e32 v208, v36, v208
	v_or_b32_e32 v210, v36, v210
	v_add_u32_e32 v212, -1, v245
	v_mad_u64_u32 v[208:209], s[100:101], v208, s29, v[48:49]
	v_mad_u64_u32 v[210:211], s[100:101], v210, s29, v[48:49]
	v_or_b32_e32 v212, v36, v212
	v_add_u32_e32 v209, v112, v209
	v_add_u32_e32 v211, v112, v211
	v_mad_u64_u32 v[212:213], s[100:101], v212, s29, v[48:49]
	v_or_b32_e32 v220, v36, v245
	global_load_dwordx4 v[216:219], v[208:209], off
	s_nop 0
	global_load_dwordx4 v[208:211], v[210:211], off
	v_add_u32_e32 v213, v112, v213
	v_mad_u64_u32 v[220:221], s[100:101], v220, s29, v[48:49]
	global_load_dwordx4 v[212:215], v[212:213], off
	v_add_u32_e32 v221, v112, v221
	global_load_dwordx4 v[220:223], v[220:221], off
	v_cmp_gt_u32_e64 s[8:9], 32, v194
	v_cmp_gt_u32_e64 s[10:11], 48, v194
	v_or_b32_e32 v26, v105, v24
	s_and_b64 s[24:25], s[8:9], s[0:1]
	s_and_b64 s[10:11], s[10:11], s[0:1]
	v_lshl_add_u32 v108, v25, 2, 0
	v_cmp_eq_u32_e64 s[0:1], 0, v26
	s_waitcnt vmcnt(6)
	v_cndmask_b32_e64 v26, v8, 0, s[24:25]
	v_cndmask_b32_e64 v117, v9, 0, s[24:25]
	v_cndmask_b32_e64 v8, v11, 0, s[24:25]
	v_cndmask_b32_e64 v111, v5, 0, s[10:11]
	v_cndmask_b32_e64 v9, v6, 0, s[10:11]
	v_cndmask_b32_e64 v5, v7, 0, s[10:11]
	ds_read_b128 v[118:121], v108
	ds_read_b128 v[122:125], v108 offset:16
	ds_read_b128 v[128:131], v108 offset:1024
	ds_read_b128 v[132:135], v108 offset:1040
	ds_read_b128 v[144:147], v108 offset:2048
	ds_read_b128 v[148:151], v108 offset:2064
	ds_read_b128 v[152:155], v108 offset:3072
	ds_read_b128 v[156:159], v108 offset:3088
	v_cndmask_b32_e64 v109, v4, 0, s[10:11]
	v_cndmask_b32_e64 v110, v10, 0, s[24:25]
	v_lshlrev_b32_e32 v4, 16, v5
	v_and_b32_e32 v5, 0xffff0000, v5
	v_lshlrev_b32_e32 v6, 16, v8
	v_and_b32_e32 v7, 0xffff0000, v8
	v_lshlrev_b32_e32 v8, 16, v9
	v_and_b32_e32 v9, 0xffff0000, v9
	v_lshlrev_b32_e32 v10, 16, v110
	v_and_b32_e32 v11, 0xffff0000, v110
	v_lshlrev_b32_e32 v110, 16, v111
	v_and_b32_e32 v111, 0xffff0000, v111
	s_waitcnt lgkmcnt(6)
	v_pk_fma_f32 v[4:5], v[124:125], v[4:5], 0 op_sel_hi:[1,1,0]
	v_pk_fma_f32 v[8:9], v[122:123], v[8:9], 0 op_sel_hi:[1,1,0]
	v_lshlrev_b32_e32 v140, 16, v117
	v_and_b32_e32 v141, 0xffff0000, v117
	v_pk_fma_f32 v[110:111], v[120:121], v[110:111], 0 op_sel_hi:[1,1,0]
	s_waitcnt lgkmcnt(4)
	v_pk_fma_f32 v[4:5], v[134:135], v[6:7], v[4:5]
	v_pk_fma_f32 v[6:7], v[132:133], v[10:11], v[8:9]
	v_pk_fma_f32 v[8:9], v[130:131], v[140:141], v[110:111]
	v_or_b32_e32 v197, 0x100, v194
	v_and_b32_e32 v47, 64, v191
	v_lshrrev_b32_e32 v198, 4, v197
	v_xor_b32_e32 v23, 1, v191
	v_add_u32_e32 v43, 64, v47
	v_cmp_lt_i32_e64 s[8:9], v23, v43
	v_mul_i32_i24_e32 v19, 0x10e00, v19
	v_add_u32_e32 v196, 0, v19
	v_cndmask_b32_e64 v23, v191, v23, s[8:9]
	v_lshlrev_b32_e32 v23, 2, v23
	v_mul_u32_u24_e32 v201, 0x110, v24
	v_or_b32_e32 v199, 0x200, v194
	v_lshrrev_b32_e32 v200, 4, v199
	v_mul_u32_u24_e32 v204, 0x110, v198
	v_or_b32_e32 v202, 0x300, v194
	v_lshrrev_b32_e32 v203, 4, v202
	v_mul_u32_u24_e32 v205, 0x110, v200
	v_mul_u32_u24_e32 v206, 0x110, v203
	s_waitcnt vmcnt(5)
	v_cndmask_b32_e64 v11, v15, 0, s[0:1]
	v_cndmask_b32_e64 v110, v13, 0, s[0:1]
	v_cndmask_b32_e64 v13, v14, 0, s[0:1]
	v_lshlrev_b32_e32 v10, 16, v11
	v_and_b32_e32 v11, 0xffff0000, v11
	v_cndmask_b32_e64 v117, v12, 0, s[0:1]
	v_lshlrev_b32_e32 v12, 16, v13
	v_and_b32_e32 v13, 0xffff0000, v13
	v_lshlrev_b32_e32 v14, 16, v110
	v_and_b32_e32 v15, 0xffff0000, v110
	s_waitcnt lgkmcnt(2)
	v_pk_fma_f32 v[4:5], v[150:151], v[10:11], v[4:5]
	s_waitcnt vmcnt(4)
	v_lshlrev_b32_e32 v10, 16, v3
	v_and_b32_e32 v11, 0xffff0000, v3
	v_pk_fma_f32 v[6:7], v[148:149], v[12:13], v[6:7]
	v_pk_fma_f32 v[8:9], v[146:147], v[14:15], v[8:9]
	v_lshlrev_b32_e32 v12, 16, v2
	v_and_b32_e32 v13, 0xffff0000, v2
	v_lshlrev_b32_e32 v2, 16, v1
	v_and_b32_e32 v3, 0xffff0000, v1
	s_waitcnt lgkmcnt(0)
	v_pk_fma_f32 v[4:5], v[158:159], v[10:11], v[4:5]
	v_pk_fma_f32 v[6:7], v[156:157], v[12:13], v[6:7]
	v_pk_fma_f32 v[110:111], v[154:155], v[2:3], v[8:9]
	v_mul_f32_e32 v1, 0xbfb8aa3b, v4
	v_mul_f32_e32 v2, 0xbfb8aa3b, v5
	v_mul_f32_e32 v3, 0xbfb8aa3b, v6
	v_exp_f32_e32 v1, v1
	v_exp_f32_e32 v2, v2
	v_exp_f32_e32 v3, v3
	v_mul_f32_e32 v9, 0xbfb8aa3b, v110
	v_exp_f32_e32 v11, v9
	v_add_f32_e32 v1, 1.0, v1
	v_add_f32_e32 v9, 1.0, v2
	v_add_f32_e32 v12, 1.0, v3
	v_rcp_f32_e32 v2, v1
	v_rcp_f32_e32 v3, v9
	v_mul_f32_e32 v8, 0xbfb8aa3b, v7
	v_exp_f32_e32 v8, v8
	v_mul_f32_e32 v10, 0xbfb8aa3b, v111
	v_pk_mul_f32 v[120:121], v[4:5], v[2:3]
	v_add_f32_e32 v2, 1.0, v11
	v_rcp_f32_e32 v130, v2
	v_lshlrev_b32_e32 v2, 16, v109
	v_and_b32_e32 v3, 0xffff0000, v109
	v_pk_fma_f32 v[2:3], v[118:119], v[2:3], 0 op_sel_hi:[1,1,0]
	v_lshlrev_b32_e32 v4, 16, v26
	v_and_b32_e32 v5, 0xffff0000, v26
	v_pk_fma_f32 v[2:3], v[128:129], v[4:5], v[2:3]
	v_lshlrev_b32_e32 v4, 16, v117
	v_and_b32_e32 v5, 0xffff0000, v117
	v_add_f32_e32 v1, 1.0, v8
	v_pk_fma_f32 v[2:3], v[144:145], v[4:5], v[2:3]
	v_lshlrev_b32_e32 v4, 16, v0
	v_and_b32_e32 v5, 0xffff0000, v0
	v_rcp_f32_e32 v9, v1
	v_exp_f32_e32 v1, v10
	v_pk_fma_f32 v[118:119], v[152:153], v[4:5], v[2:3]
	v_rcp_f32_e32 v8, v12
	v_mul_f32_e32 v0, 0xbfb8aa3b, v118
	v_exp_f32_e32 v26, v0
	v_add_f32_e32 v126, 1.0, v1
	v_pk_mul_f32 v[124:125], v[6:7], v[8:9]
	s_nop 0
	v_add_u32_e32 v226, -3, v200
	v_add_u32_e32 v228, -2, v200
	v_or_b32_e32 v226, v36, v226
	v_or_b32_e32 v228, v36, v228
	v_add_u32_e32 v230, -1, v200
	v_mad_u64_u32 v[226:227], s[100:101], v226, s29, v[48:49]
	v_mad_u64_u32 v[228:229], s[100:101], v228, s29, v[48:49]
	v_or_b32_e32 v230, v36, v230
	v_add_u32_e32 v227, v112, v227
	v_add_u32_e32 v229, v112, v229
	v_mad_u64_u32 v[230:231], s[100:101], v230, s29, v[48:49]
	v_or_b32_e32 v238, v36, v200
	global_load_dwordx4 v[234:237], v[226:227], off
	s_nop 0
	global_load_dwordx4 v[226:229], v[228:229], off
	v_add_u32_e32 v231, v112, v231
	v_mad_u64_u32 v[238:239], s[100:101], v238, s29, v[48:49]
	global_load_dwordx4 v[230:233], v[230:231], off
	v_add_u32_e32 v239, v112, v239
	global_load_dwordx4 v[238:241], v[238:239], off
	v_mul_f32_e32 v109, 0xbfb8aa3b, v119
	v_exp_f32_e32 v109, v109
	v_add_f32_e32 v26, 1.0, v26
	v_rcp_f32_e32 v128, v26
	v_rcp_f32_e32 v131, v126
	v_add_f32_e32 v26, 1.0, v109
	v_rcp_f32_e32 v129, v26
	v_pk_mul_f32 v[132:133], v[124:125], v[124:125]
	v_pk_mul_f32 v[130:131], v[110:111], v[130:131]
	v_pk_mul_f32 v[122:123], v[120:121], v[120:121]
	v_pk_mul_f32 v[118:119], v[118:119], v[128:129]
	v_pk_mul_f32 v[110:111], v[130:131], v[130:131]
	v_pk_mul_f32 v[128:129], v[118:119], v[118:119]
	v_xor_b32_e32 v109, 2, v191
	v_add_f32_e32 v26, v128, v129
	v_add_f32_e32 v26, v110, v26
	v_add_f32_e32 v26, v111, v26
	v_add_f32_e32 v26, v132, v26
	v_add_f32_e32 v26, v133, v26
	v_add_f32_e32 v26, v122, v26
	v_add_f32_e32 v26, v123, v26
	ds_bpermute_b32 v110, v23, v26
	v_cmp_lt_i32_e64 s[8:9], v109, v43
	s_waitcnt lgkmcnt(0)
	v_add_f32_e32 v26, v26, v110
	v_cndmask_b32_e64 v109, v191, v109, s[8:9]
	v_lshlrev_b32_e32 v109, 2, v109
	ds_bpermute_b32 v111, v109, v26
	v_xor_b32_e32 v110, 4, v191
	v_cmp_lt_i32_e64 s[8:9], v110, v43
	s_waitcnt lgkmcnt(0)
	v_add_f32_e32 v26, v26, v111
	v_cndmask_b32_e64 v110, v191, v110, s[8:9]
	v_lshlrev_b32_e32 v110, 2, v110
	ds_bpermute_b32 v117, v110, v26
	v_xor_b32_e32 v111, 8, v191
	v_cmp_lt_i32_e64 s[8:9], v111, v43
	s_waitcnt lgkmcnt(0)
	v_add_f32_e32 v26, v26, v117
	v_cndmask_b32_e64 v43, v191, v111, s[8:9]
	v_lshlrev_b32_e32 v111, 2, v43
	ds_bpermute_b32 v43, v111, v26
	s_waitcnt lgkmcnt(0)
	v_add_f32_e32 v26, v26, v43
	v_add_f32_e32 v26, 0x358637bd, v26
	v_mul_f32_e32 v43, 0x4b800000, v26
	v_cmp_gt_f32_e64 s[8:9], s70, v26
	s_waitcnt vmcnt(7)
	v_lshlrev_b32_e32 v140, 16, v219
	v_cndmask_b32_e64 v26, v26, v43, s[8:9]
	v_rsq_f32_e32 v26, v26
	v_and_b32_e32 v141, 0xffff0000, v219
	v_mul_f32_e32 v19, 0x45800000, v26
	v_cndmask_b32_e64 v19, v26, v19, s[8:9]
	v_mul_f32_e32 v26, 0x3db504f3, v19
	v_pk_mul_f32 v[118:119], v[118:119], v[26:27] op_sel_hi:[1,0]
	v_pk_mul_f32 v[122:123], v[130:131], v[26:27] op_sel_hi:[1,0]
	v_pk_mul_f32 v[124:125], v[124:125], v[26:27] op_sel_hi:[1,0]
	v_pk_mul_f32 v[128:129], v[120:121], v[26:27] op_sel_hi:[1,0]
	v_lshlrev_b32_e32 v26, 1, v25
	v_cvt_pk_bf16_f32 v118, v118, v119
	v_cvt_pk_bf16_f32 v119, v122, v123
	v_cvt_pk_bf16_f32 v120, v124, v125
	v_cvt_pk_bf16_f32 v121, v128, v129
	v_add3_u32 v117, v196, v201, v26
	ds_write_b128 v117, v[118:121] offset:4096
	ds_read_b128 v[118:121], v108 offset:16
	ds_read_b128 v[122:125], v108 offset:1040
	ds_read_b128 v[128:131], v108 offset:2064
	ds_read_b128 v[132:135], v108 offset:3088
	ds_read_b128 v[144:147], v108
	s_waitcnt lgkmcnt(4)
	v_pk_fma_f32 v[120:121], v[120:121], v[140:141], 0 op_sel_hi:[1,1,0]
	s_waitcnt vmcnt(6)
	v_lshlrev_b32_e32 v140, 16, v211
	v_and_b32_e32 v141, 0xffff0000, v211
	s_waitcnt lgkmcnt(3)
	v_pk_fma_f32 v[120:121], v[124:125], v[140:141], v[120:121]
	s_waitcnt vmcnt(5)
	v_lshlrev_b32_e32 v124, 16, v215
	v_and_b32_e32 v125, 0xffff0000, v215
	s_waitcnt lgkmcnt(2)
	v_pk_fma_f32 v[120:121], v[130:131], v[124:125], v[120:121]
	s_waitcnt vmcnt(4)
	v_lshlrev_b32_e32 v124, 16, v223
	v_and_b32_e32 v125, 0xffff0000, v223
	s_waitcnt lgkmcnt(1)
	v_pk_fma_f32 v[120:121], v[134:135], v[124:125], v[120:121]
	ds_read_b128 v[148:151], v108 offset:1024
	ds_read_b128 v[152:155], v108 offset:2048
	ds_read_b128 v[156:159], v108 offset:3072
	v_mul_f32_e32 v3, 0xbfb8aa3b, v120
	v_exp_f32_e32 v3, v3
	v_mul_f32_e32 v7, 0xbfb8aa3b, v121
	v_exp_f32_e32 v7, v7
	v_and_b32_e32 v15, 0xffff0000, v209
	v_add_f32_e32 v3, 1.0, v3
	v_rcp_f32_e32 v124, v3
	v_add_f32_e32 v3, 1.0, v7
	v_rcp_f32_e32 v125, v3
	v_and_b32_e32 v7, 0xffff0000, v222
	v_pk_mul_f32 v[120:121], v[120:121], v[124:125]
	v_lshlrev_b32_e32 v124, 16, v218
	v_and_b32_e32 v125, 0xffff0000, v218
	v_pk_fma_f32 v[10:11], v[118:119], v[124:125], 0 op_sel_hi:[1,1,0]
	v_lshlrev_b32_e32 v118, 16, v210
	v_and_b32_e32 v119, 0xffff0000, v210
	v_pk_fma_f32 v[2:3], v[122:123], v[118:119], v[10:11]
	v_lshlrev_b32_e32 v10, 16, v214
	v_and_b32_e32 v11, 0xffff0000, v214
	v_pk_fma_f32 v[2:3], v[128:129], v[10:11], v[2:3]
	v_lshlrev_b32_e32 v6, 16, v222
	v_pk_fma_f32 v[2:3], v[132:133], v[6:7], v[2:3]
	v_lshlrev_b32_e32 v10, 16, v217
	v_mul_f32_e32 v6, 0xbfb8aa3b, v2
	v_mul_f32_e32 v7, 0xbfb8aa3b, v3
	v_exp_f32_e32 v6, v6
	v_exp_f32_e32 v7, v7
	v_and_b32_e32 v11, 0xffff0000, v217
	s_waitcnt lgkmcnt(3)
	v_pk_fma_f32 v[10:11], v[146:147], v[10:11], 0 op_sel_hi:[1,1,0]
	v_lshlrev_b32_e32 v14, 16, v209
	s_waitcnt lgkmcnt(2)
	v_pk_fma_f32 v[10:11], v[150:151], v[14:15], v[10:11]
	v_lshlrev_b32_e32 v14, 16, v213
	v_and_b32_e32 v15, 0xffff0000, v213
	s_waitcnt lgkmcnt(1)
	v_pk_fma_f32 v[10:11], v[154:155], v[14:15], v[10:11]
	v_lshlrev_b32_e32 v14, 16, v221
	v_and_b32_e32 v15, 0xffff0000, v221
	v_add_f32_e32 v6, 1.0, v6
	v_add_f32_e32 v7, 1.0, v7
	s_waitcnt lgkmcnt(0)
	v_pk_fma_f32 v[122:123], v[158:159], v[14:15], v[10:11]
	v_rcp_f32_e32 v6, v6
	v_rcp_f32_e32 v7, v7
	v_mul_f32_e32 v1, 0xbfb8aa3b, v122
	v_exp_f32_e32 v1, v1
	v_mul_f32_e32 v5, 0xbfb8aa3b, v123
	v_pk_mul_f32 v[124:125], v[2:3], v[6:7]
	v_lshlrev_b32_e32 v2, 16, v216
	v_and_b32_e32 v3, 0xffff0000, v216
	v_add_f32_e32 v1, 1.0, v1
	v_pk_fma_f32 v[2:3], v[144:145], v[2:3], 0 op_sel_hi:[1,1,0]
	v_lshlrev_b32_e32 v6, 16, v208
	v_and_b32_e32 v7, 0xffff0000, v208
	v_rcp_f32_e32 v128, v1
	v_pk_fma_f32 v[0:1], v[148:149], v[6:7], v[2:3]
	v_lshlrev_b32_e32 v2, 16, v212
	v_and_b32_e32 v3, 0xffff0000, v212
	v_exp_f32_e32 v5, v5
	v_pk_fma_f32 v[0:1], v[152:153], v[2:3], v[0:1]
	v_lshlrev_b32_e32 v2, 16, v220
	v_and_b32_e32 v3, 0xffff0000, v220
	v_pk_fma_f32 v[130:131], v[156:157], v[2:3], v[0:1]
	v_add_f32_e32 v19, 1.0, v5
	s_nop 0
	v_add_u32_e32 v208, -3, v203
	v_add_u32_e32 v210, -2, v203
	v_or_b32_e32 v208, v36, v208
	v_or_b32_e32 v210, v36, v210
	v_add_u32_e32 v212, -1, v203
	v_mad_u64_u32 v[208:209], s[100:101], v208, s29, v[48:49]
	v_mad_u64_u32 v[210:211], s[100:101], v210, s29, v[48:49]
	v_or_b32_e32 v212, v36, v212
	v_add_u32_e32 v209, v112, v209
	v_add_u32_e32 v211, v112, v211
	v_mad_u64_u32 v[212:213], s[100:101], v212, s29, v[48:49]
	v_or_b32_e32 v220, v36, v203
	global_load_dwordx4 v[216:219], v[208:209], off
	s_nop 0
	global_load_dwordx4 v[208:211], v[210:211], off
	v_add_u32_e32 v213, v112, v213
	v_mad_u64_u32 v[220:221], s[100:101], v220, s29, v[48:49]
	global_load_dwordx4 v[212:215], v[212:213], off
	v_add_u32_e32 v221, v112, v221
	global_load_dwordx4 v[220:223], v[220:221], off
	v_mul_f32_e32 v25, 0xbfb8aa3b, v130
	v_exp_f32_e32 v25, v25
	v_mul_f32_e32 v43, 0xbfb8aa3b, v131
	v_exp_f32_e32 v43, v43
	v_rcp_f32_e32 v129, v19
	v_add_f32_e32 v19, 1.0, v25
	v_rcp_f32_e32 v132, v19
	v_add_f32_e32 v19, 1.0, v43
	v_rcp_f32_e32 v133, v19
	v_pk_mul_f32 v[122:123], v[122:123], v[128:129]
	v_pk_mul_f32 v[134:135], v[124:125], v[124:125]
	v_pk_mul_f32 v[128:129], v[122:123], v[122:123]
	v_pk_mul_f32 v[130:131], v[130:131], v[132:133]
	v_pk_mul_f32 v[118:119], v[120:121], v[120:121]
	v_pk_mul_f32 v[132:133], v[130:131], v[130:131]
	s_waitcnt vmcnt(7)
	v_lshlrev_b32_e32 v140, 16, v237
	v_add_f32_e32 v19, v132, v133
	v_add_f32_e32 v19, v128, v19
	v_add_f32_e32 v19, v129, v19
	v_add_f32_e32 v19, v134, v19
	v_add_f32_e32 v19, v135, v19
	v_add_f32_e32 v19, v118, v19
	v_add_f32_e32 v19, v119, v19
	ds_bpermute_b32 v25, v23, v19
	v_and_b32_e32 v141, 0xffff0000, v237
	s_waitcnt lgkmcnt(0)
	v_add_f32_e32 v19, v19, v25
	ds_bpermute_b32 v25, v109, v19
	s_waitcnt lgkmcnt(0)
	v_add_f32_e32 v19, v19, v25
	ds_bpermute_b32 v25, v110, v19
	s_waitcnt lgkmcnt(0)
	v_add_f32_e32 v19, v19, v25
	ds_bpermute_b32 v25, v111, v19
	s_waitcnt lgkmcnt(0)
	v_add_f32_e32 v19, v19, v25
	v_add_f32_e32 v19, 0x358637bd, v19
	v_mul_f32_e32 v25, 0x4b800000, v19
	v_cmp_gt_f32_e64 s[8:9], s70, v19
	s_nop 1
	v_cndmask_b32_e64 v19, v19, v25, s[8:9]
	v_rsq_f32_e32 v19, v19
	s_nop 0
	v_mul_f32_e32 v25, 0x45800000, v19
	v_cndmask_b32_e64 v19, v19, v25, s[8:9]
	v_mul_f32_e32 v118, 0x3db504f3, v19
	v_pk_mul_f32 v[128:129], v[130:131], v[118:119] op_sel_hi:[1,0]
	v_pk_mul_f32 v[122:123], v[122:123], v[118:119] op_sel_hi:[1,0]
	v_pk_mul_f32 v[124:125], v[124:125], v[118:119] op_sel_hi:[1,0]
	v_pk_mul_f32 v[130:131], v[120:121], v[118:119] op_sel_hi:[1,0]
	v_cvt_pk_bf16_f32 v118, v128, v129
	v_cvt_pk_bf16_f32 v119, v122, v123
	v_cvt_pk_bf16_f32 v120, v124, v125
	v_cvt_pk_bf16_f32 v121, v130, v131
	v_add3_u32 v19, v196, v204, v26
	ds_write_b128 v19, v[118:121] offset:4096
	ds_read_b128 v[118:121], v108 offset:16
	ds_read_b128 v[122:125], v108 offset:1040
	ds_read_b128 v[128:131], v108 offset:2064
	ds_read_b128 v[132:135], v108 offset:3088
	ds_read_b128 v[144:147], v108
	s_waitcnt lgkmcnt(4)
	v_pk_fma_f32 v[120:121], v[120:121], v[140:141], 0 op_sel_hi:[1,1,0]
	s_waitcnt vmcnt(6)
	v_lshlrev_b32_e32 v140, 16, v229
	v_and_b32_e32 v141, 0xffff0000, v229
	s_waitcnt lgkmcnt(3)
	v_pk_fma_f32 v[120:121], v[124:125], v[140:141], v[120:121]
	s_waitcnt vmcnt(5)
	v_lshlrev_b32_e32 v124, 16, v233
	v_and_b32_e32 v125, 0xffff0000, v233
	s_waitcnt lgkmcnt(2)
	v_pk_fma_f32 v[120:121], v[130:131], v[124:125], v[120:121]
	s_waitcnt vmcnt(4)
	v_lshlrev_b32_e32 v124, 16, v241
	v_and_b32_e32 v125, 0xffff0000, v241
	s_waitcnt lgkmcnt(1)
	v_pk_fma_f32 v[120:121], v[134:135], v[124:125], v[120:121]
	ds_read_b128 v[148:151], v108 offset:1024
	ds_read_b128 v[152:155], v108 offset:2048
	ds_read_b128 v[156:159], v108 offset:3072
	v_mul_f32_e32 v3, 0xbfb8aa3b, v120
	v_exp_f32_e32 v3, v3
	v_mul_f32_e32 v7, 0xbfb8aa3b, v121
	v_exp_f32_e32 v7, v7
	v_and_b32_e32 v15, 0xffff0000, v227
	v_add_f32_e32 v3, 1.0, v3
	v_rcp_f32_e32 v124, v3
	v_add_f32_e32 v3, 1.0, v7
	v_rcp_f32_e32 v125, v3
	v_and_b32_e32 v7, 0xffff0000, v240
	v_pk_mul_f32 v[120:121], v[120:121], v[124:125]
	v_lshlrev_b32_e32 v124, 16, v236
	v_and_b32_e32 v125, 0xffff0000, v236
	v_pk_fma_f32 v[10:11], v[118:119], v[124:125], 0 op_sel_hi:[1,1,0]
	v_lshlrev_b32_e32 v118, 16, v228
	v_and_b32_e32 v119, 0xffff0000, v228
	v_pk_fma_f32 v[2:3], v[122:123], v[118:119], v[10:11]
	v_lshlrev_b32_e32 v10, 16, v232
	v_and_b32_e32 v11, 0xffff0000, v232
	v_pk_fma_f32 v[2:3], v[128:129], v[10:11], v[2:3]
	v_lshlrev_b32_e32 v6, 16, v240
	v_pk_fma_f32 v[2:3], v[132:133], v[6:7], v[2:3]
	v_lshlrev_b32_e32 v10, 16, v235
	v_mul_f32_e32 v6, 0xbfb8aa3b, v2
	v_mul_f32_e32 v7, 0xbfb8aa3b, v3
	v_exp_f32_e32 v6, v6
	v_exp_f32_e32 v7, v7
	v_and_b32_e32 v11, 0xffff0000, v235
	s_waitcnt lgkmcnt(3)
	v_pk_fma_f32 v[10:11], v[146:147], v[10:11], 0 op_sel_hi:[1,1,0]
	v_lshlrev_b32_e32 v14, 16, v227
	s_waitcnt lgkmcnt(2)
	v_pk_fma_f32 v[10:11], v[150:151], v[14:15], v[10:11]
	v_lshlrev_b32_e32 v14, 16, v231
	v_and_b32_e32 v15, 0xffff0000, v231
	s_waitcnt lgkmcnt(1)
	v_pk_fma_f32 v[10:11], v[154:155], v[14:15], v[10:11]
	v_lshlrev_b32_e32 v14, 16, v239
	v_and_b32_e32 v15, 0xffff0000, v239
	v_add_f32_e32 v6, 1.0, v6
	v_add_f32_e32 v7, 1.0, v7
	s_waitcnt lgkmcnt(0)
	v_pk_fma_f32 v[122:123], v[158:159], v[14:15], v[10:11]
	v_rcp_f32_e32 v6, v6
	v_rcp_f32_e32 v7, v7
	v_mul_f32_e32 v1, 0xbfb8aa3b, v122
	v_exp_f32_e32 v1, v1
	v_mul_f32_e32 v5, 0xbfb8aa3b, v123
	v_pk_mul_f32 v[124:125], v[2:3], v[6:7]
	v_lshlrev_b32_e32 v2, 16, v234
	v_and_b32_e32 v3, 0xffff0000, v234
	v_add_f32_e32 v1, 1.0, v1
	v_pk_fma_f32 v[2:3], v[144:145], v[2:3], 0 op_sel_hi:[1,1,0]
	v_lshlrev_b32_e32 v6, 16, v226
	v_and_b32_e32 v7, 0xffff0000, v226
	v_rcp_f32_e32 v128, v1
	v_pk_fma_f32 v[0:1], v[148:149], v[6:7], v[2:3]
	v_lshlrev_b32_e32 v2, 16, v230
	v_and_b32_e32 v3, 0xffff0000, v230
	v_exp_f32_e32 v5, v5
	v_pk_fma_f32 v[0:1], v[152:153], v[2:3], v[0:1]
	v_lshlrev_b32_e32 v2, 16, v238
	v_and_b32_e32 v3, 0xffff0000, v238
	v_pk_fma_f32 v[130:131], v[156:157], v[2:3], v[0:1]
	v_add_f32_e32 v19, 1.0, v5
	s_nop 0
	v_mul_f32_e32 v25, 0xbfb8aa3b, v130
	v_exp_f32_e32 v25, v25
	v_mul_f32_e32 v43, 0xbfb8aa3b, v131
	v_exp_f32_e32 v43, v43
	v_rcp_f32_e32 v129, v19
	v_add_f32_e32 v19, 1.0, v25
	v_rcp_f32_e32 v48, v19
	v_add_f32_e32 v19, 1.0, v43
	v_rcp_f32_e32 v49, v19
	v_pk_mul_f32 v[122:123], v[122:123], v[128:129]
	v_pk_mul_f32 v[132:133], v[124:125], v[124:125]
	v_pk_mul_f32 v[128:129], v[122:123], v[122:123]
	v_pk_mul_f32 v[48:49], v[130:131], v[48:49]
	v_pk_mul_f32 v[118:119], v[120:121], v[120:121]
	v_pk_mul_f32 v[130:131], v[48:49], v[48:49]
	s_nop 0
	v_add_f32_e32 v19, v130, v131
	v_add_f32_e32 v19, v128, v19
	v_add_f32_e32 v19, v129, v19
	v_add_f32_e32 v19, v132, v19
	v_add_f32_e32 v19, v133, v19
	v_add_f32_e32 v19, v118, v19
	v_add_f32_e32 v19, v119, v19
	ds_bpermute_b32 v25, v23, v19
	s_waitcnt lgkmcnt(0)
	v_add_f32_e32 v19, v19, v25
	ds_bpermute_b32 v25, v109, v19
	s_waitcnt lgkmcnt(0)
	v_add_f32_e32 v19, v19, v25
	ds_bpermute_b32 v25, v110, v19
	s_waitcnt lgkmcnt(0)
	v_add_f32_e32 v19, v19, v25
	ds_bpermute_b32 v25, v111, v19
	s_waitcnt lgkmcnt(0)
	v_add_f32_e32 v19, v19, v25
	v_add_f32_e32 v19, 0x358637bd, v19
	v_mul_f32_e32 v25, 0x4b800000, v19
	v_cmp_gt_f32_e64 s[8:9], s70, v19
	s_nop 1
	v_cndmask_b32_e64 v19, v19, v25, s[8:9]
	v_rsq_f32_e32 v19, v19
	s_nop 0
	v_mul_f32_e32 v25, 0x45800000, v19
	v_cndmask_b32_e64 v19, v19, v25, s[8:9]
	v_mul_f32_e32 v118, 0x3db504f3, v19
	v_pk_mul_f32 v[48:49], v[48:49], v[118:119] op_sel_hi:[1,0]
	v_pk_mul_f32 v[122:123], v[122:123], v[118:119] op_sel_hi:[1,0]
	v_pk_mul_f32 v[124:125], v[124:125], v[118:119] op_sel_hi:[1,0]
	v_pk_mul_f32 v[128:129], v[120:121], v[118:119] op_sel_hi:[1,0]
	v_cvt_pk_bf16_f32 v118, v48, v49
	v_cvt_pk_bf16_f32 v119, v122, v123
	v_cvt_pk_bf16_f32 v120, v124, v125
	v_cvt_pk_bf16_f32 v121, v128, v129
	v_add3_u32 v19, v196, v205, v26
	ds_write_b128 v19, v[118:121] offset:4096
	ds_read_b128 v[118:121], v108 offset:16
	ds_read_b128 v[122:125], v108 offset:1040
	ds_read_b128 v[128:131], v108 offset:2064
	ds_read_b128 v[132:135], v108 offset:3088
	ds_read_b128 v[144:147], v108
	s_waitcnt vmcnt(3)
	v_lshlrev_b32_e32 v48, 16, v219
	v_and_b32_e32 v49, 0xffff0000, v219
	s_waitcnt lgkmcnt(4)
	v_pk_fma_f32 v[48:49], v[120:121], v[48:49], 0 op_sel_hi:[1,1,0]
	s_waitcnt vmcnt(2)
	v_lshlrev_b32_e32 v120, 16, v211
	v_and_b32_e32 v121, 0xffff0000, v211
	s_waitcnt lgkmcnt(3)
	v_pk_fma_f32 v[48:49], v[124:125], v[120:121], v[48:49]
	s_waitcnt vmcnt(1)
	v_lshlrev_b32_e32 v120, 16, v215
	v_and_b32_e32 v121, 0xffff0000, v215
	s_waitcnt lgkmcnt(2)
	v_pk_fma_f32 v[48:49], v[130:131], v[120:121], v[48:49]
	s_waitcnt vmcnt(0)
	v_lshlrev_b32_e32 v120, 16, v223
	v_and_b32_e32 v121, 0xffff0000, v223
	s_waitcnt lgkmcnt(1)
	v_pk_fma_f32 v[48:49], v[134:135], v[120:121], v[48:49]
	ds_read_b128 v[148:151], v108 offset:1024
	ds_read_b128 v[152:155], v108 offset:2048
	ds_read_b128 v[156:159], v108 offset:3072
	v_mul_f32_e32 v3, 0xbfb8aa3b, v48
	v_exp_f32_e32 v3, v3
	v_mul_f32_e32 v7, 0xbfb8aa3b, v49
	v_exp_f32_e32 v7, v7
	v_and_b32_e32 v15, 0xffff0000, v217
	v_add_f32_e32 v3, 1.0, v3
	v_rcp_f32_e32 v120, v3
	v_add_f32_e32 v3, 1.0, v7
	v_rcp_f32_e32 v121, v3
	v_and_b32_e32 v7, 0xffff0000, v222
	v_mov_b32_e32 v25, v21
	v_pk_mul_f32 v[48:49], v[48:49], v[120:121]
	v_lshlrev_b32_e32 v120, 16, v218
	v_and_b32_e32 v121, 0xffff0000, v218
	v_pk_fma_f32 v[10:11], v[118:119], v[120:121], 0 op_sel_hi:[1,1,0]
	v_lshlrev_b32_e32 v118, 16, v210
	v_and_b32_e32 v119, 0xffff0000, v210
	v_pk_fma_f32 v[2:3], v[122:123], v[118:119], v[10:11]
	v_lshlrev_b32_e32 v10, 16, v214
	v_and_b32_e32 v11, 0xffff0000, v214
	v_pk_fma_f32 v[2:3], v[128:129], v[10:11], v[2:3]
	v_lshlrev_b32_e32 v6, 16, v222
	v_pk_fma_f32 v[2:3], v[132:133], v[6:7], v[2:3]
	v_lshlrev_b32_e32 v14, 16, v217
	v_mul_f32_e32 v6, 0xbfb8aa3b, v2
	v_exp_f32_e32 v10, v6
	v_mul_f32_e32 v6, 0xbfb8aa3b, v3
	s_waitcnt lgkmcnt(3)
	v_pk_fma_f32 v[14:15], v[146:147], v[14:15], 0 op_sel_hi:[1,1,0]
	v_lshlrev_b32_e32 v118, 16, v209
	v_and_b32_e32 v119, 0xffff0000, v209
	v_exp_f32_e32 v11, v6
	s_waitcnt lgkmcnt(2)
	v_pk_fma_f32 v[14:15], v[150:151], v[118:119], v[14:15]
	v_lshlrev_b32_e32 v118, 16, v213
	v_and_b32_e32 v119, 0xffff0000, v213
	s_waitcnt lgkmcnt(1)
	v_pk_fma_f32 v[14:15], v[154:155], v[118:119], v[14:15]
	v_lshlrev_b32_e32 v118, 16, v221
	v_and_b32_e32 v119, 0xffff0000, v221
	s_waitcnt lgkmcnt(0)
	v_pk_fma_f32 v[14:15], v[158:159], v[118:119], v[14:15]
	v_add_f32_e32 v10, 1.0, v10
	v_mul_f32_e32 v1, 0xbfb8aa3b, v14
	v_add_f32_e32 v11, 1.0, v11
	v_exp_f32_e32 v1, v1
	v_rcp_f32_e32 v10, v10
	v_rcp_f32_e32 v11, v11
	v_mul_f32_e32 v5, 0xbfb8aa3b, v15
	v_exp_f32_e32 v5, v5
	v_lshlrev_b32_e32 v118, 16, v216
	v_and_b32_e32 v119, 0xffff0000, v216
	v_add_f32_e32 v1, 1.0, v1
	v_pk_fma_f32 v[8:9], v[144:145], v[118:119], 0 op_sel_hi:[1,1,0]
	v_lshlrev_b32_e32 v118, 16, v208
	v_and_b32_e32 v119, 0xffff0000, v208
	v_pk_mul_f32 v[2:3], v[2:3], v[10:11]
	v_rcp_f32_e32 v10, v1
	v_pk_fma_f32 v[0:1], v[148:149], v[118:119], v[8:9]
	v_lshlrev_b32_e32 v8, 16, v212
	v_and_b32_e32 v9, 0xffff0000, v212
	v_add_f32_e32 v11, 1.0, v5
	v_pk_fma_f32 v[0:1], v[152:153], v[8:9], v[0:1]
	v_lshlrev_b32_e32 v4, 16, v220
	v_and_b32_e32 v5, 0xffff0000, v220
	v_pk_fma_f32 v[0:1], v[156:157], v[4:5], v[0:1]
	v_rcp_f32_e32 v11, v11
	v_mul_f32_e32 v4, 0xbfb8aa3b, v0
	v_mul_f32_e32 v5, 0xbfb8aa3b, v1
	v_exp_f32_e32 v4, v4
	v_exp_f32_e32 v5, v5
	v_pk_mul_f32 v[10:11], v[14:15], v[10:11]
	v_pk_mul_f32 v[8:9], v[2:3], v[2:3]
	v_add_f32_e32 v4, 1.0, v4
	v_add_f32_e32 v5, 1.0, v5
	v_rcp_f32_e32 v4, v4
	v_rcp_f32_e32 v5, v5
	v_pk_mul_f32 v[12:13], v[10:11], v[10:11]
	v_pk_mul_f32 v[6:7], v[48:49], v[48:49]
	v_pk_mul_f32 v[0:1], v[0:1], v[4:5]
	s_nop 0
	v_pk_mul_f32 v[4:5], v[0:1], v[0:1]
	s_nop 0
	v_add_f32_e32 v4, v4, v5
	v_add_f32_e32 v4, v12, v4
	v_add_f32_e32 v4, v13, v4
	v_add_f32_e32 v4, v8, v4
	v_add_f32_e32 v4, v9, v4
	v_add_f32_e32 v4, v6, v4
	v_add_f32_e32 v4, v7, v4
	ds_bpermute_b32 v5, v23, v4
	s_waitcnt lgkmcnt(0)
	v_add_f32_e32 v4, v4, v5
	ds_bpermute_b32 v5, v109, v4
	s_waitcnt lgkmcnt(0)
	v_add_f32_e32 v4, v4, v5
	ds_bpermute_b32 v5, v110, v4
	s_waitcnt lgkmcnt(0)
	v_add_f32_e32 v4, v4, v5
	ds_bpermute_b32 v5, v111, v4
	s_waitcnt lgkmcnt(0)
	v_add_f32_e32 v4, v4, v5
	v_add_f32_e32 v4, 0x358637bd, v4
	v_mul_f32_e32 v5, 0x4b800000, v4
	v_cmp_gt_f32_e64 s[8:9], s70, v4
	s_nop 1
	v_cndmask_b32_e64 v4, v4, v5, s[8:9]
	v_rsq_f32_e32 v4, v4
	s_nop 0
	v_mul_f32_e32 v5, 0x45800000, v4
	v_cndmask_b32_e64 v4, v4, v5, s[8:9]
	v_mul_f32_e32 v4, 0x3db504f3, v4
	v_pk_mul_f32 v[0:1], v[0:1], v[4:5] op_sel_hi:[1,0]
	v_pk_mul_f32 v[6:7], v[10:11], v[4:5] op_sel_hi:[1,0]
	v_pk_mul_f32 v[2:3], v[2:3], v[4:5] op_sel_hi:[1,0]
	v_pk_mul_f32 v[4:5], v[48:49], v[4:5] op_sel_hi:[1,0]
	v_cvt_pk_bf16_f32 v0, v0, v1
	v_cvt_pk_bf16_f32 v1, v6, v7
	v_cvt_pk_bf16_f32 v2, v2, v3
	v_cvt_pk_bf16_f32 v3, v4, v5
	v_add3_u32 v4, v196, v206, v26
	ds_write_b128 v4, v[0:3] offset:4096
	v_mov_b64_e32 v[2:3], 0x20600000
	v_mov_b64_e32 v[0:1], 0x5000
	v_mov_b64_e32 v[4:5], v[24:25]
	s_and_saveexec_b64 s[8:9], vcc
	v_mov_b32_e32 v19, v21
	v_mov_b64_e32 v[2:3], 0x8100000
	v_mov_b64_e32 v[0:1], 0x6000
	v_mov_b64_e32 v[4:5], v[18:19]
	v_mov_b64_e32 v[16:17], v[36:37]
	s_or_b64 exec, exec, s[8:9]
	v_mad_u64_u32 v[6:7], s[8:9], v46, v114, 0
	v_add_u32_e32 v7, v7, v20
	v_lshl_or_b32 v20, v113, 1, v192
	v_lshl_add_u64 v[2:3], s[82:83], 0, v[2:3]
	v_lshl_add_u64 v[2:3], v[2:3], 0, v[20:21]
	v_lshl_add_u64 v[4:5], v[16:17], 0, v[4:5]
	v_mad_u64_u32 v[2:3], s[8:9], v4, v0, v[2:3]
	v_lshl_add_u64 v[10:11], s[14:15], 0, v[20:21]
	v_lshl_add_u64 v[12:13], s[68:69], 0, v[20:21]
	v_mov_b32_e32 v4, v3
	v_mad_u64_u32 v[0:1], s[8:9], v5, v0, v[4:5]
	v_cndmask_b32_e64 v5, v11, v13, s[4:5]
	v_cndmask_b32_e64 v4, v10, v12, s[4:5]
	v_mov_b32_e32 v3, v0
	v_lshl_add_u64 v[4:5], v[4:5], 0, v[6:7]
	global_load_dwordx4 v[0:3], v[2:3], off
	s_nop 0
	global_load_dwordx4 v[4:7], v[4:5], off
	s_and_saveexec_b64 s[4:5], s[6:7]
	s_xor_b64 s[4:5], exec, s[4:5]
	v_mov_b32_e32 v43, v21
	v_lshl_add_u64 v[10:11], v[36:37], 0, v[42:43]
	v_mad_u64_u32 v[8:9], s[6:7], v10, s29, v[12:13]
	v_mov_b32_e32 v10, v9
	v_mad_u64_u32 v[10:11], s[6:7], v11, s29, v[10:11]
	v_mov_b32_e32 v9, v10
	s_andn2_saveexec_b64 s[4:5], s[4:5]
	v_lshl_add_u64 v[8:9], v[10:11], 0, v[44:45]
	s_mov_b64 s[6:7], 0xa000
	v_lshl_add_u64 v[8:9], v[8:9], 0, s[6:7]
	s_or_b64 exec, exec, s[4:5]
	global_load_dwordx4 v[8:11], v[8:9], off
	v_mad_u64_u32 v[14:15], s[4:5], v115, s29, 0
	v_add_u32_e32 v15, v15, v112
	v_lshl_add_u64 v[14:15], v[12:13], 0, v[14:15]
	global_load_dwordx4 v[14:17], v[14:15], off
	v_or_b32_e32 v244, 16, v24
	v_or_b32_e32 v240, v36, v244
	v_mad_u64_u32 v[240:241], s[100:101], v240, s29, v[12:13]
	v_add_u32_e32 v241, v112, v241
	global_load_dwordx4 v[240:243], v[240:241], off
	v_add_u32_e32 v226, 13, v24
	v_or_b32_e32 v226, v36, v226
	v_add_u32_e32 v230, 14, v24
	v_mad_u64_u32 v[226:227], s[100:101], v226, s29, v[12:13]
	v_or_b32_e32 v230, v36, v230
	v_add_u32_e32 v234, 15, v24
	v_add_u32_e32 v227, v112, v227
	v_mad_u64_u32 v[230:231], s[100:101], v230, s29, v[12:13]
	v_or_b32_e32 v234, v36, v234
	global_load_dwordx4 v[226:229], v[226:227], off
	v_add_u32_e32 v231, v112, v231
	v_mad_u64_u32 v[234:235], s[100:101], v234, s29, v[12:13]
	global_load_dwordx4 v[230:233], v[230:231], off
	v_add_u32_e32 v235, v112, v235
	global_load_dwordx4 v[234:237], v[234:235], off
	s_waitcnt vmcnt(6)
	v_cndmask_b32_e64 v113, v4, 0, s[24:25]
	v_cndmask_b32_e64 v114, v5, 0, s[24:25]
	v_cndmask_b32_e64 v115, v6, 0, s[24:25]
	v_cndmask_b32_e64 v126, v7, 0, s[24:25]
	v_cndmask_b32_e64 v140, v0, 0, s[10:11]
	v_cndmask_b32_e64 v141, v1, 0, s[10:11]
	v_cndmask_b32_e64 v144, v2, 0, s[10:11]
	v_cndmask_b32_e64 v19, v3, 0, s[10:11]
	v_lshlrev_b32_e32 v18, 16, v19
	v_and_b32_e32 v19, 0xffff0000, v19
	v_bfe_u32 v20, v38, 6, 2
	s_waitcnt vmcnt(5)
	v_cndmask_b32_e64 v25, v8, 0, s[0:1]
	v_cndmask_b32_e64 v46, v9, 0, s[0:1]
	v_cndmask_b32_e64 v48, v10, 0, s[0:1]
	v_cndmask_b32_e64 v49, v11, 0, s[0:1]
	ds_read_b128 v[0:3], v108 offset:512
	ds_read_b128 v[4:7], v108 offset:528
	ds_read_b128 v[8:11], v108 offset:1536
	ds_read_b128 v[42:45], v108 offset:1552
	ds_read_b128 v[118:121], v108 offset:2560
	ds_read_b128 v[122:125], v108 offset:2576
	ds_read_b128 v[128:131], v108 offset:3584
	ds_read_b128 v[132:135], v108 offset:3600
	s_waitcnt lgkmcnt(6)
	v_pk_fma_f32 v[6:7], v[6:7], v[18:19], 0 op_sel_hi:[1,1,0]
	v_lshlrev_b32_e32 v18, 16, v126
	v_and_b32_e32 v19, 0xffff0000, v126
	s_waitcnt lgkmcnt(4)
	v_pk_fma_f32 v[6:7], v[44:45], v[18:19], v[6:7]
	v_lshlrev_b32_e32 v18, 16, v49
	v_and_b32_e32 v19, 0xffff0000, v49
	s_waitcnt lgkmcnt(2)
	v_pk_fma_f32 v[6:7], v[124:125], v[18:19], v[6:7]
	s_waitcnt vmcnt(4)
	v_lshlrev_b32_e32 v18, 16, v17
	v_and_b32_e32 v19, 0xffff0000, v17
	v_lshlrev_b32_e32 v44, 16, v144
	v_and_b32_e32 v45, 0xffff0000, v144
	s_waitcnt lgkmcnt(0)
	v_pk_fma_f32 v[6:7], v[134:135], v[18:19], v[6:7]
	v_pk_fma_f32 v[4:5], v[4:5], v[44:45], 0 op_sel_hi:[1,1,0]
	v_lshlrev_b32_e32 v44, 16, v115
	v_and_b32_e32 v45, 0xffff0000, v115
	v_mul_f32_e32 v17, 0xbfb8aa3b, v6
	v_pk_fma_f32 v[4:5], v[42:43], v[44:45], v[4:5]
	v_lshlrev_b32_e32 v42, 16, v48
	v_and_b32_e32 v43, 0xffff0000, v48
	v_exp_f32_e32 v17, v17
	v_pk_fma_f32 v[4:5], v[122:123], v[42:43], v[4:5]
	v_lshlrev_b32_e32 v42, 16, v16
	v_and_b32_e32 v43, 0xffff0000, v16
	v_pk_fma_f32 v[4:5], v[132:133], v[42:43], v[4:5]
	v_lshlrev_b32_e32 v42, 16, v141
	v_and_b32_e32 v43, 0xffff0000, v141
	v_pk_fma_f32 v[2:3], v[2:3], v[42:43], 0 op_sel_hi:[1,1,0]
	v_lshlrev_b32_e32 v42, 16, v114
	v_and_b32_e32 v43, 0xffff0000, v114
	v_pk_fma_f32 v[2:3], v[10:11], v[42:43], v[2:3]
	v_lshlrev_b32_e32 v42, 16, v140
	v_and_b32_e32 v43, 0xffff0000, v140
	v_add_f32_e32 v17, 1.0, v17
	v_pk_fma_f32 v[0:1], v[0:1], v[42:43], 0 op_sel_hi:[1,1,0]
	v_lshlrev_b32_e32 v42, 16, v113
	v_and_b32_e32 v43, 0xffff0000, v113
	v_rcp_f32_e32 v18, v17
	v_mul_f32_e32 v17, 0xbfb8aa3b, v7
	v_pk_fma_f32 v[0:1], v[8:9], v[42:43], v[0:1]
	v_lshlrev_b32_e32 v8, 16, v25
	v_and_b32_e32 v9, 0xffff0000, v25
	v_exp_f32_e32 v17, v17
	v_lshlrev_b32_e32 v10, 16, v46
	v_and_b32_e32 v11, 0xffff0000, v46
	v_pk_fma_f32 v[0:1], v[118:119], v[8:9], v[0:1]
	v_lshlrev_b32_e32 v8, 16, v14
	v_and_b32_e32 v9, 0xffff0000, v14
	v_pk_fma_f32 v[2:3], v[120:121], v[10:11], v[2:3]
	v_lshlrev_b32_e32 v10, 16, v15
	v_and_b32_e32 v11, 0xffff0000, v15
	v_pk_fma_f32 v[0:1], v[128:129], v[8:9], v[0:1]
	v_pk_fma_f32 v[2:3], v[130:131], v[10:11], v[2:3]
	v_mul_f32_e32 v8, 0xbfb8aa3b, v0
	v_mul_f32_e32 v9, 0xbfb8aa3b, v1
	v_mul_f32_e32 v10, 0xbfb8aa3b, v2
	v_mul_f32_e32 v11, 0xbfb8aa3b, v3
	v_exp_f32_e32 v8, v8
	v_exp_f32_e32 v9, v9
	v_add_f32_e32 v17, 1.0, v17
	v_exp_f32_e32 v10, v10
	v_exp_f32_e32 v11, v11
	v_rcp_f32_e32 v19, v17
	v_mul_f32_e32 v16, 0xbfb8aa3b, v4
	v_mul_f32_e32 v17, 0xbfb8aa3b, v5
	v_exp_f32_e32 v16, v16
	v_exp_f32_e32 v17, v17
	v_add_f32_e32 v8, 1.0, v8
	v_add_f32_e32 v9, 1.0, v9
	v_add_f32_e32 v10, 1.0, v10
	v_add_f32_e32 v11, 1.0, v11
	v_rcp_f32_e32 v8, v8
	v_rcp_f32_e32 v9, v9
	v_rcp_f32_e32 v10, v10
	v_rcp_f32_e32 v11, v11
	v_add_f32_e32 v16, 1.0, v16
	v_add_f32_e32 v17, 1.0, v17
	v_rcp_f32_e32 v16, v16
	v_rcp_f32_e32 v17, v17
	v_pk_mul_f32 v[0:1], v[0:1], v[8:9]
	v_pk_mul_f32 v[2:3], v[2:3], v[10:11]
	v_pk_mul_f32 v[8:9], v[0:1], v[0:1]
	v_pk_mul_f32 v[10:11], v[2:3], v[2:3]
	v_add_f32_e32 v8, v8, v9
	v_pk_mul_f32 v[4:5], v[4:5], v[16:17]
	v_add_f32_e32 v8, v10, v8
	v_pk_mul_f32 v[16:17], v[4:5], v[4:5]
	v_add_f32_e32 v8, v11, v8
	v_pk_mul_f32 v[6:7], v[6:7], v[18:19]
	v_add_f32_e32 v8, v16, v8
	v_pk_mul_f32 v[18:19], v[6:7], v[6:7]
	v_add_f32_e32 v8, v17, v8
	v_add_f32_e32 v8, v18, v8
	v_add_f32_e32 v8, v19, v8
	ds_bpermute_b32 v9, v23, v8
	v_or_b32_e32 v25, 16, v24
	s_waitcnt lgkmcnt(0)
	v_add_f32_e32 v8, v8, v9
	ds_bpermute_b32 v9, v109, v8
	s_waitcnt lgkmcnt(0)
	v_add_f32_e32 v8, v8, v9
	ds_bpermute_b32 v9, v110, v8
	s_waitcnt lgkmcnt(0)
	v_add_f32_e32 v8, v8, v9
	ds_bpermute_b32 v9, v111, v8
	s_waitcnt lgkmcnt(0)
	v_add_f32_e32 v8, v8, v9
	v_add_f32_e32 v8, 0x358637bd, v8
	v_cmp_gt_f32_e32 vcc, s70, v8
	v_mul_f32_e32 v9, 0x4b800000, v8
	s_nop 0
	v_cndmask_b32_e32 v8, v8, v9, vcc
	v_rsq_f32_e32 v8, v8
	s_nop 0
	v_mul_f32_e32 v9, 0x45800000, v8
	v_cndmask_b32_e32 v8, v8, v9, vcc
	v_pk_mul_f32 v[0:1], v[0:1], v[8:9] op_sel_hi:[1,0]
	v_pk_mul_f32 v[2:3], v[2:3], v[8:9] op_sel_hi:[1,0]
	v_pk_mul_f32 v[4:5], v[4:5], v[8:9] op_sel_hi:[1,0]
	v_pk_mul_f32 v[6:7], v[6:7], v[8:9] op_sel_hi:[1,0]
	v_cvt_pk_bf16_f32 v0, v0, v1
	v_cvt_pk_bf16_f32 v1, v2, v3
	v_cvt_pk_bf16_f32 v2, v4, v5
	v_cvt_pk_bf16_f32 v3, v6, v7
	ds_write_b128 v117, v[0:3] offset:21504
	v_add_u32_e32 v216, 31, v24
	v_or_b32_e32 v216, v36, v216
	v_mad_u64_u32 v[216:217], s[100:101], v216, s29, v[12:13]
	v_or3_b32 v222, v24, v36, 32
	v_add_u32_e32 v217, v112, v217
	v_mad_u64_u32 v[222:223], s[100:101], v222, s29, v[12:13]
	v_add_u32_e32 v223, v112, v223
	global_load_dwordx4 v[222:225], v[222:223], off
	v_add_u32_e32 v208, 29, v24
	v_or_b32_e32 v208, v36, v208
	v_add_u32_e32 v212, 30, v24
	v_mad_u64_u32 v[208:209], s[100:101], v208, s29, v[12:13]
	v_or_b32_e32 v212, v36, v212
	v_add_u32_e32 v209, v112, v209
	v_mad_u64_u32 v[212:213], s[100:101], v212, s29, v[12:13]
	global_load_dwordx4 v[208:211], v[208:209], off
	v_add_u32_e32 v213, v112, v213
	global_load_dwordx4 v[212:215], v[212:213], off
	s_nop 0
	global_load_dwordx4 v[216:219], v[216:217], off
	ds_read_b128 v[42:45], v108 offset:512
	ds_read_b128 v[118:121], v108 offset:528
	ds_read_b128 v[122:125], v108 offset:1536
	ds_read_b128 v[128:131], v108 offset:1552
	ds_read_b128 v[132:135], v108 offset:2560
	ds_read_b128 v[144:147], v108 offset:2576
	ds_read_b128 v[148:151], v108 offset:3584
	ds_read_b128 v[152:155], v108 offset:3600
	s_waitcnt vmcnt(6)
	v_lshlrev_b32_e32 v18, 16, v229
	v_and_b32_e32 v19, 0xffff0000, v229
	s_waitcnt lgkmcnt(6)
	v_pk_fma_f32 v[18:19], v[120:121], v[18:19], 0 op_sel_hi:[1,1,0]
	v_lshlrev_b32_e32 v114, 16, v228
	s_waitcnt vmcnt(5)
	v_lshlrev_b32_e32 v48, 16, v233
	v_and_b32_e32 v49, 0xffff0000, v233
	s_waitcnt lgkmcnt(4)
	v_pk_fma_f32 v[18:19], v[130:131], v[48:49], v[18:19]
	s_waitcnt vmcnt(4)
	v_lshlrev_b32_e32 v48, 16, v237
	v_and_b32_e32 v49, 0xffff0000, v237
	s_waitcnt lgkmcnt(2)
	v_pk_fma_f32 v[18:19], v[146:147], v[48:49], v[18:19]
	v_lshlrev_b32_e32 v48, 16, v243
	v_and_b32_e32 v49, 0xffff0000, v243
	s_waitcnt lgkmcnt(0)
	v_pk_fma_f32 v[18:19], v[154:155], v[48:49], v[18:19]
	v_and_b32_e32 v115, 0xffff0000, v228
	v_mul_f32_e32 v3, 0xbfb8aa3b, v18
	v_exp_f32_e32 v3, v3
	v_and_b32_e32 v7, 0xffff0000, v236
	v_and_b32_e32 v11, 0xffff0000, v227
	v_and_b32_e32 v17, 0xffff0000, v231
	v_add_f32_e32 v3, 1.0, v3
	v_rcp_f32_e32 v48, v3
	v_mul_f32_e32 v3, 0xbfb8aa3b, v19
	v_exp_f32_e32 v3, v3
	s_nop 0
	v_add_f32_e32 v3, 1.0, v3
	v_rcp_f32_e32 v49, v3
	v_pk_fma_f32 v[2:3], v[118:119], v[114:115], 0 op_sel_hi:[1,1,0]
	v_lshlrev_b32_e32 v114, 16, v232
	v_and_b32_e32 v115, 0xffff0000, v232
	v_pk_fma_f32 v[2:3], v[128:129], v[114:115], v[2:3]
	v_lshlrev_b32_e32 v6, 16, v236
	v_lshlrev_b32_e32 v10, 16, v227
	v_pk_fma_f32 v[2:3], v[144:145], v[6:7], v[2:3]
	v_lshlrev_b32_e32 v6, 16, v242
	v_and_b32_e32 v7, 0xffff0000, v242
	v_pk_fma_f32 v[10:11], v[44:45], v[10:11], 0 op_sel_hi:[1,1,0]
	v_lshlrev_b32_e32 v16, 16, v231
	v_pk_fma_f32 v[10:11], v[124:125], v[16:17], v[10:11]
	v_lshlrev_b32_e32 v16, 16, v235
	v_and_b32_e32 v17, 0xffff0000, v235
	v_pk_fma_f32 v[10:11], v[134:135], v[16:17], v[10:11]
	v_lshlrev_b32_e32 v16, 16, v241
	v_and_b32_e32 v17, 0xffff0000, v241
	v_pk_fma_f32 v[10:11], v[150:151], v[16:17], v[10:11]
	v_lshlrev_b32_e32 v44, 16, v226
	v_mul_f32_e32 v1, 0xbfb8aa3b, v10
	v_exp_f32_e32 v1, v1
	v_and_b32_e32 v45, 0xffff0000, v226
	v_and_b32_e32 v5, 0xffff0000, v234
	v_pk_fma_f32 v[2:3], v[152:153], v[6:7], v[2:3]
	v_add_f32_e32 v1, 1.0, v1
	v_rcp_f32_e32 v16, v1
	v_mul_f32_e32 v1, 0xbfb8aa3b, v11
	v_exp_f32_e32 v1, v1
	v_mul_f32_e32 v6, 0xbfb8aa3b, v2
	v_mul_f32_e32 v7, 0xbfb8aa3b, v3
	v_exp_f32_e32 v6, v6
	v_add_f32_e32 v1, 1.0, v1
	v_rcp_f32_e32 v17, v1
	v_pk_fma_f32 v[0:1], v[42:43], v[44:45], 0 op_sel_hi:[1,1,0]
	v_lshlrev_b32_e32 v42, 16, v230
	v_and_b32_e32 v43, 0xffff0000, v230
	v_pk_fma_f32 v[0:1], v[122:123], v[42:43], v[0:1]
	v_lshlrev_b32_e32 v4, 16, v234
	v_pk_fma_f32 v[0:1], v[132:133], v[4:5], v[0:1]
	v_lshlrev_b32_e32 v4, 16, v240
	v_and_b32_e32 v5, 0xffff0000, v240
	v_pk_fma_f32 v[0:1], v[148:149], v[4:5], v[0:1]
	v_exp_f32_e32 v7, v7
	v_mul_f32_e32 v4, 0xbfb8aa3b, v0
	v_mul_f32_e32 v5, 0xbfb8aa3b, v1
	v_exp_f32_e32 v4, v4
	v_exp_f32_e32 v5, v5
	v_add_f32_e32 v6, 1.0, v6
	v_add_f32_e32 v7, 1.0, v7
	v_add_f32_e32 v4, 1.0, v4
	v_add_f32_e32 v5, 1.0, v5
	v_rcp_f32_e32 v4, v4
	v_rcp_f32_e32 v5, v5
	v_rcp_f32_e32 v6, v6
	v_rcp_f32_e32 v7, v7
	v_pk_mul_f32 v[10:11], v[10:11], v[16:17]
	v_pk_mul_f32 v[0:1], v[0:1], v[4:5]
	v_pk_mul_f32 v[16:17], v[10:11], v[10:11]
	v_pk_mul_f32 v[4:5], v[0:1], v[0:1]
	v_pk_mul_f32 v[2:3], v[2:3], v[6:7]
	v_add_f32_e32 v4, v4, v5
	v_add_f32_e32 v4, v16, v4
	v_pk_mul_f32 v[6:7], v[2:3], v[2:3]
	v_add_f32_e32 v4, v17, v4
	v_pk_mul_f32 v[18:19], v[18:19], v[48:49]
	v_add_f32_e32 v4, v6, v4
	v_pk_mul_f32 v[48:49], v[18:19], v[18:19]
	v_add_f32_e32 v4, v7, v4
	v_add_f32_e32 v4, v48, v4
	v_add_f32_e32 v4, v49, v4
	ds_bpermute_b32 v5, v23, v4
	s_waitcnt lgkmcnt(0)
	v_add_f32_e32 v4, v4, v5
	ds_bpermute_b32 v5, v109, v4
	s_waitcnt lgkmcnt(0)
	v_add_f32_e32 v4, v4, v5
	ds_bpermute_b32 v5, v110, v4
	s_waitcnt lgkmcnt(0)
	v_add_f32_e32 v4, v4, v5
	ds_bpermute_b32 v5, v111, v4
	s_waitcnt lgkmcnt(0)
	v_add_f32_e32 v4, v4, v5
	v_add_f32_e32 v4, 0x358637bd, v4
	v_cmp_gt_f32_e32 vcc, s70, v4
	v_mul_f32_e32 v5, 0x4b800000, v4
	s_nop 0
	v_cndmask_b32_e32 v4, v4, v5, vcc
	v_rsq_f32_e32 v4, v4
	s_nop 0
	v_mul_f32_e32 v5, 0x45800000, v4
	v_cndmask_b32_e32 v4, v4, v5, vcc
	v_pk_mul_f32 v[0:1], v[0:1], v[4:5] op_sel_hi:[1,0]
	v_pk_mul_f32 v[6:7], v[10:11], v[4:5] op_sel_hi:[1,0]
	v_pk_mul_f32 v[2:3], v[2:3], v[4:5] op_sel_hi:[1,0]
	v_pk_mul_f32 v[4:5], v[18:19], v[4:5] op_sel_hi:[1,0]
	v_cvt_pk_bf16_f32 v2, v2, v3
	v_cvt_pk_bf16_f32 v3, v4, v5
	v_mul_u32_u24_e32 v4, 0x110, v25
	v_cvt_pk_bf16_f32 v0, v0, v1
	v_cvt_pk_bf16_f32 v1, v6, v7
	v_add3_u32 v25, v196, v4, v26
	ds_write_b128 v25, v[0:3] offset:21504
	s_waitcnt vmcnt(2)
	v_lshlrev_b32_e32 v18, 16, v211
	v_bfe_u32 v234, v38, 4, 4
	v_add_u32_e32 v226, 45, v234
	v_or_b32_e32 v226, v36, v226
	v_add_u32_e32 v230, 46, v234
	v_or_b32_e32 v244, 48, v234
	v_mad_u64_u32 v[226:227], s[100:101], v226, s29, v[12:13]
	v_or_b32_e32 v230, v36, v230
	v_add_u32_e32 v234, 47, v234
	v_add_u32_e32 v227, v112, v227
	v_mad_u64_u32 v[230:231], s[100:101], v230, s29, v[12:13]
	v_or_b32_e32 v234, v36, v234
	global_load_dwordx4 v[226:229], v[226:227], off
	v_add_u32_e32 v231, v112, v231
	v_mad_u64_u32 v[234:235], s[100:101], v234, s29, v[12:13]
	v_or_b32_e32 v240, v36, v244
	global_load_dwordx4 v[230:233], v[230:231], off
	v_add_u32_e32 v235, v112, v235
	v_mad_u64_u32 v[238:239], s[100:101], v240, s29, v[12:13]
	global_load_dwordx4 v[234:237], v[234:235], off
	v_add_u32_e32 v239, v112, v239
	global_load_dwordx4 v[238:241], v[238:239], off
	ds_read_b128 v[42:45], v108 offset:512
	ds_read_b128 v[118:121], v108 offset:528
	ds_read_b128 v[122:125], v108 offset:1536
	ds_read_b128 v[128:131], v108 offset:1552
	ds_read_b128 v[132:135], v108 offset:2560
	ds_read_b128 v[144:147], v108 offset:2576
	ds_read_b128 v[148:151], v108 offset:3584
	ds_read_b128 v[152:155], v108 offset:3600
	v_and_b32_e32 v19, 0xffff0000, v211
	s_waitcnt lgkmcnt(6)
	v_pk_fma_f32 v[18:19], v[120:121], v[18:19], 0 op_sel_hi:[1,1,0]
	s_waitcnt vmcnt(5)
	v_lshlrev_b32_e32 v48, 16, v215
	v_and_b32_e32 v49, 0xffff0000, v215
	s_waitcnt lgkmcnt(4)
	v_pk_fma_f32 v[18:19], v[130:131], v[48:49], v[18:19]
	v_lshlrev_b32_e32 v114, 16, v210
	v_and_b32_e32 v115, 0xffff0000, v210
	s_waitcnt vmcnt(4)
	v_lshlrev_b32_e32 v48, 16, v219
	v_and_b32_e32 v49, 0xffff0000, v219
	s_waitcnt lgkmcnt(2)
	v_pk_fma_f32 v[18:19], v[146:147], v[48:49], v[18:19]
	v_lshlrev_b32_e32 v48, 16, v225
	v_and_b32_e32 v49, 0xffff0000, v225
	s_waitcnt lgkmcnt(0)
	v_pk_fma_f32 v[18:19], v[154:155], v[48:49], v[18:19]
	v_and_b32_e32 v7, 0xffff0000, v218
	v_mul_f32_e32 v3, 0xbfb8aa3b, v18
	v_exp_f32_e32 v3, v3
	v_and_b32_e32 v11, 0xffff0000, v209
	v_and_b32_e32 v17, 0xffff0000, v213
	v_add_f32_e32 v3, 1.0, v3
	v_rcp_f32_e32 v48, v3
	v_mul_f32_e32 v3, 0xbfb8aa3b, v19
	v_exp_f32_e32 v3, v3
	s_nop 0
	v_add_f32_e32 v3, 1.0, v3
	v_rcp_f32_e32 v49, v3
	v_pk_fma_f32 v[2:3], v[118:119], v[114:115], 0 op_sel_hi:[1,1,0]
	v_lshlrev_b32_e32 v114, 16, v214
	v_and_b32_e32 v115, 0xffff0000, v214
	v_pk_fma_f32 v[2:3], v[128:129], v[114:115], v[2:3]
	v_lshlrev_b32_e32 v6, 16, v218
	v_lshlrev_b32_e32 v10, 16, v209
	v_pk_fma_f32 v[2:3], v[144:145], v[6:7], v[2:3]
	v_lshlrev_b32_e32 v6, 16, v224
	v_and_b32_e32 v7, 0xffff0000, v224
	v_pk_fma_f32 v[10:11], v[44:45], v[10:11], 0 op_sel_hi:[1,1,0]
	v_lshlrev_b32_e32 v16, 16, v213
	v_pk_fma_f32 v[10:11], v[124:125], v[16:17], v[10:11]
	v_lshlrev_b32_e32 v16, 16, v217
	v_and_b32_e32 v17, 0xffff0000, v217
	v_pk_fma_f32 v[10:11], v[134:135], v[16:17], v[10:11]
	v_lshlrev_b32_e32 v16, 16, v223
	v_and_b32_e32 v17, 0xffff0000, v223
	v_pk_fma_f32 v[10:11], v[150:151], v[16:17], v[10:11]
	v_lshlrev_b32_e32 v44, 16, v208
	v_mul_f32_e32 v1, 0xbfb8aa3b, v10
	v_exp_f32_e32 v1, v1
	v_and_b32_e32 v45, 0xffff0000, v208
	v_and_b32_e32 v5, 0xffff0000, v216
	v_pk_fma_f32 v[2:3], v[152:153], v[6:7], v[2:3]
	v_add_f32_e32 v1, 1.0, v1
	v_rcp_f32_e32 v16, v1
	v_mul_f32_e32 v1, 0xbfb8aa3b, v11
	v_exp_f32_e32 v1, v1
	v_mul_f32_e32 v6, 0xbfb8aa3b, v2
	v_mul_f32_e32 v7, 0xbfb8aa3b, v3
	v_exp_f32_e32 v6, v6
	v_add_f32_e32 v1, 1.0, v1
	v_rcp_f32_e32 v17, v1
	v_pk_fma_f32 v[0:1], v[42:43], v[44:45], 0 op_sel_hi:[1,1,0]
	v_lshlrev_b32_e32 v42, 16, v212
	v_and_b32_e32 v43, 0xffff0000, v212
	v_pk_fma_f32 v[0:1], v[122:123], v[42:43], v[0:1]
	v_lshlrev_b32_e32 v4, 16, v216
	v_pk_fma_f32 v[0:1], v[132:133], v[4:5], v[0:1]
	v_lshlrev_b32_e32 v4, 16, v222
	v_and_b32_e32 v5, 0xffff0000, v222
	v_pk_fma_f32 v[0:1], v[148:149], v[4:5], v[0:1]
	v_exp_f32_e32 v7, v7
	v_mul_f32_e32 v4, 0xbfb8aa3b, v0
	v_mul_f32_e32 v5, 0xbfb8aa3b, v1
	v_exp_f32_e32 v4, v4
	v_exp_f32_e32 v5, v5
	v_add_f32_e32 v6, 1.0, v6
	v_add_f32_e32 v7, 1.0, v7
	v_add_f32_e32 v4, 1.0, v4
	v_add_f32_e32 v5, 1.0, v5
	v_rcp_f32_e32 v4, v4
	v_rcp_f32_e32 v5, v5
	v_rcp_f32_e32 v6, v6
	v_rcp_f32_e32 v7, v7
	v_pk_mul_f32 v[10:11], v[10:11], v[16:17]
	v_pk_mul_f32 v[0:1], v[0:1], v[4:5]
	v_pk_mul_f32 v[16:17], v[10:11], v[10:11]
	v_pk_mul_f32 v[4:5], v[0:1], v[0:1]
	v_pk_mul_f32 v[2:3], v[2:3], v[6:7]
	v_add_f32_e32 v4, v4, v5
	v_add_f32_e32 v4, v16, v4
	v_pk_mul_f32 v[6:7], v[2:3], v[2:3]
	v_add_f32_e32 v4, v17, v4
	v_pk_mul_f32 v[18:19], v[18:19], v[48:49]
	v_add_f32_e32 v4, v6, v4
	v_pk_mul_f32 v[48:49], v[18:19], v[18:19]
	v_add_f32_e32 v4, v7, v4
	v_add_f32_e32 v4, v48, v4
	v_add_f32_e32 v4, v49, v4
	ds_bpermute_b32 v5, v23, v4
	v_bfe_u32 v8, v38, 4, 4
	s_waitcnt lgkmcnt(0)
	v_add_f32_e32 v4, v4, v5
	ds_bpermute_b32 v5, v109, v4
	s_waitcnt lgkmcnt(0)
	v_add_f32_e32 v4, v4, v5
	ds_bpermute_b32 v5, v110, v4
	s_waitcnt lgkmcnt(0)
	v_add_f32_e32 v4, v4, v5
	ds_bpermute_b32 v5, v111, v4
	s_waitcnt lgkmcnt(0)
	v_add_f32_e32 v4, v4, v5
	v_add_f32_e32 v4, 0x358637bd, v4
	v_cmp_gt_f32_e32 vcc, s70, v4
	v_mul_f32_e32 v5, 0x4b800000, v4
	s_nop 0
	v_cndmask_b32_e32 v4, v4, v5, vcc
	v_rsq_f32_e32 v4, v4
	s_nop 0
	v_mul_f32_e32 v5, 0x45800000, v4
	v_cndmask_b32_e32 v4, v4, v5, vcc
	v_pk_mul_f32 v[0:1], v[0:1], v[4:5] op_sel_hi:[1,0]
	v_pk_mul_f32 v[6:7], v[10:11], v[4:5] op_sel_hi:[1,0]
	v_pk_mul_f32 v[2:3], v[2:3], v[4:5] op_sel_hi:[1,0]
	v_pk_mul_f32 v[4:5], v[18:19], v[4:5] op_sel_hi:[1,0]
	v_cvt_pk_bf16_f32 v0, v0, v1
	v_cvt_pk_bf16_f32 v1, v6, v7
	v_cvt_pk_bf16_f32 v2, v2, v3
	v_cvt_pk_bf16_f32 v3, v4, v5
	ds_write_b128 v25, v[0:3] offset:25856
	v_or_b32_e32 v25, 48, v8
	ds_read_b128 v[16:19], v108 offset:512
	ds_read_b128 v[42:45], v108 offset:528
	ds_read_b128 v[112:115], v108 offset:1536
	ds_read_b128 v[118:121], v108 offset:1552
	ds_read_b128 v[122:125], v108 offset:2560
	ds_read_b128 v[128:131], v108 offset:2576
	ds_read_b128 v[132:135], v108 offset:3584
	ds_read_b128 v[144:147], v108 offset:3600
	s_waitcnt vmcnt(3)
	v_lshlrev_b32_e32 v48, 16, v229
	v_and_b32_e32 v49, 0xffff0000, v229
	s_waitcnt lgkmcnt(6)
	v_pk_fma_f32 v[44:45], v[44:45], v[48:49], 0 op_sel_hi:[1,1,0]
	s_waitcnt vmcnt(2)
	v_lshlrev_b32_e32 v48, 16, v233
	v_and_b32_e32 v49, 0xffff0000, v233
	s_waitcnt lgkmcnt(4)
	v_pk_fma_f32 v[44:45], v[120:121], v[48:49], v[44:45]
	v_lshlrev_b32_e32 v120, 16, v228
	s_waitcnt vmcnt(1)
	v_lshlrev_b32_e32 v48, 16, v237
	v_and_b32_e32 v49, 0xffff0000, v237
	s_waitcnt lgkmcnt(2)
	v_pk_fma_f32 v[44:45], v[130:131], v[48:49], v[44:45]
	s_waitcnt vmcnt(0)
	v_lshlrev_b32_e32 v48, 16, v241
	v_and_b32_e32 v49, 0xffff0000, v241
	s_waitcnt lgkmcnt(0)
	v_pk_fma_f32 v[44:45], v[146:147], v[48:49], v[44:45]
	v_and_b32_e32 v121, 0xffff0000, v228
	v_mul_f32_e32 v3, 0xbfb8aa3b, v44
	v_exp_f32_e32 v3, v3
	v_and_b32_e32 v7, 0xffff0000, v236
	v_and_b32_e32 v11, 0xffff0000, v227
	v_and_b32_e32 v15, 0xffff0000, v231
	v_add_f32_e32 v3, 1.0, v3
	v_rcp_f32_e32 v48, v3
	v_mul_f32_e32 v3, 0xbfb8aa3b, v45
	v_exp_f32_e32 v3, v3
	s_nop 0
	v_add_f32_e32 v3, 1.0, v3
	v_rcp_f32_e32 v49, v3
	v_pk_fma_f32 v[2:3], v[42:43], v[120:121], 0 op_sel_hi:[1,1,0]
	v_lshlrev_b32_e32 v42, 16, v232
	v_and_b32_e32 v43, 0xffff0000, v232
	v_pk_fma_f32 v[2:3], v[118:119], v[42:43], v[2:3]
	v_lshlrev_b32_e32 v6, 16, v236
	v_lshlrev_b32_e32 v10, 16, v227
	v_pk_fma_f32 v[2:3], v[128:129], v[6:7], v[2:3]
	v_lshlrev_b32_e32 v6, 16, v240
	v_and_b32_e32 v7, 0xffff0000, v240
	v_pk_fma_f32 v[10:11], v[18:19], v[10:11], 0 op_sel_hi:[1,1,0]
	v_lshlrev_b32_e32 v14, 16, v231
	v_pk_fma_f32 v[10:11], v[114:115], v[14:15], v[10:11]
	v_lshlrev_b32_e32 v14, 16, v235
	v_and_b32_e32 v15, 0xffff0000, v235
	v_pk_fma_f32 v[10:11], v[124:125], v[14:15], v[10:11]
	v_lshlrev_b32_e32 v14, 16, v239
	v_and_b32_e32 v15, 0xffff0000, v239
	v_pk_fma_f32 v[10:11], v[134:135], v[14:15], v[10:11]
	v_lshlrev_b32_e32 v18, 16, v226
	v_mul_f32_e32 v1, 0xbfb8aa3b, v10
	v_exp_f32_e32 v1, v1
	v_and_b32_e32 v19, 0xffff0000, v226
	v_and_b32_e32 v5, 0xffff0000, v234
	v_pk_fma_f32 v[2:3], v[144:145], v[6:7], v[2:3]
	v_add_f32_e32 v1, 1.0, v1
	v_rcp_f32_e32 v14, v1
	v_mul_f32_e32 v1, 0xbfb8aa3b, v11
	v_exp_f32_e32 v1, v1
	v_mul_f32_e32 v6, 0xbfb8aa3b, v2
	v_mul_f32_e32 v7, 0xbfb8aa3b, v3
	v_exp_f32_e32 v6, v6
	v_add_f32_e32 v1, 1.0, v1
	v_rcp_f32_e32 v15, v1
	v_pk_fma_f32 v[0:1], v[16:17], v[18:19], 0 op_sel_hi:[1,1,0]
	v_lshlrev_b32_e32 v16, 16, v230
	v_and_b32_e32 v17, 0xffff0000, v230
	v_pk_fma_f32 v[0:1], v[112:113], v[16:17], v[0:1]
	v_lshlrev_b32_e32 v4, 16, v234
	v_pk_fma_f32 v[0:1], v[122:123], v[4:5], v[0:1]
	v_lshlrev_b32_e32 v4, 16, v238
	v_and_b32_e32 v5, 0xffff0000, v238
	v_pk_fma_f32 v[0:1], v[132:133], v[4:5], v[0:1]
	v_exp_f32_e32 v7, v7
	v_mul_f32_e32 v4, 0xbfb8aa3b, v0
	v_mul_f32_e32 v5, 0xbfb8aa3b, v1
	v_exp_f32_e32 v4, v4
	v_exp_f32_e32 v5, v5
	v_add_f32_e32 v6, 1.0, v6
	v_add_f32_e32 v7, 1.0, v7
	v_add_f32_e32 v4, 1.0, v4
	v_add_f32_e32 v5, 1.0, v5
	v_rcp_f32_e32 v4, v4
	v_rcp_f32_e32 v5, v5
	v_rcp_f32_e32 v6, v6
	v_rcp_f32_e32 v7, v7
	v_pk_mul_f32 v[10:11], v[10:11], v[14:15]
	v_pk_mul_f32 v[0:1], v[0:1], v[4:5]
	v_pk_mul_f32 v[14:15], v[10:11], v[10:11]
	v_pk_mul_f32 v[4:5], v[0:1], v[0:1]
	v_pk_mul_f32 v[2:3], v[2:3], v[6:7]
	v_add_f32_e32 v4, v4, v5
	v_add_f32_e32 v4, v14, v4
	v_pk_mul_f32 v[6:7], v[2:3], v[2:3]
	v_add_f32_e32 v4, v15, v4
	v_pk_mul_f32 v[44:45], v[44:45], v[48:49]
	v_add_f32_e32 v4, v6, v4
	v_pk_mul_f32 v[48:49], v[44:45], v[44:45]
	v_add_f32_e32 v4, v7, v4
	v_add_f32_e32 v4, v48, v4
	v_add_f32_e32 v4, v49, v4
	ds_bpermute_b32 v5, v23, v4
	v_lshlrev_b32_e32 v16, 5, v40
	s_waitcnt lgkmcnt(0)
	v_add_f32_e32 v4, v4, v5
	ds_bpermute_b32 v5, v109, v4
	s_waitcnt lgkmcnt(0)
	v_add_f32_e32 v4, v4, v5
	ds_bpermute_b32 v5, v110, v4
	s_waitcnt lgkmcnt(0)
	v_add_f32_e32 v4, v4, v5
	ds_bpermute_b32 v5, v111, v4
	s_waitcnt lgkmcnt(0)
	v_add_f32_e32 v4, v4, v5
	v_add_f32_e32 v4, 0x358637bd, v4
	v_cmp_gt_f32_e32 vcc, s70, v4
	v_mul_f32_e32 v5, 0x4b800000, v4
	s_nop 0
	v_cndmask_b32_e32 v4, v4, v5, vcc
	v_rsq_f32_e32 v4, v4
	s_nop 0
	v_mul_f32_e32 v5, 0x45800000, v4
	v_cndmask_b32_e32 v4, v4, v5, vcc
	v_pk_mul_f32 v[0:1], v[0:1], v[4:5] op_sel_hi:[1,0]
	v_pk_mul_f32 v[6:7], v[10:11], v[4:5] op_sel_hi:[1,0]
	v_pk_mul_f32 v[2:3], v[2:3], v[4:5] op_sel_hi:[1,0]
	v_pk_mul_f32 v[4:5], v[44:45], v[4:5] op_sel_hi:[1,0]
	v_cvt_pk_bf16_f32 v2, v2, v3
	v_cvt_pk_bf16_f32 v3, v4, v5
	v_mul_u32_u24_e32 v4, 0x110, v25
	v_cvt_pk_bf16_f32 v0, v0, v1
	v_cvt_pk_bf16_f32 v1, v6, v7
	v_add3_u32 v4, v196, v4, v26
	ds_write_b128 v4, v[0:3] offset:21504
	v_cmp_lt_u32_e32 vcc, 1, v20
	v_add_u32_e32 v2, 0x5400, v196
	s_and_saveexec_b64 s[0:1], vcc
	s_xor_b64 s[0:1], exec, s[0:1]
	v_add_u32_e32 v2, 0x1000, v196
	v_lshlrev_b32_e32 v16, 5, v40
	s_or_saveexec_b64 s[0:1], s[0:1]
	v_mov_b32_e32 v23, v37
	v_and_b32_e32 v14, 63, v38
	v_add_u32_e32 v15, 0x11800, v196
	v_add_u32_e32 v12, 0x11c00, v196
	v_add_u32_e32 v13, 0x11a00, v196
	v_mov_b32_e32 v0, 0xc800
	s_xor_b64 exec, exec, s[0:1]
	s_cbranch_execz .LBB0_293
	v_or_b32_e32 v3, v107, v20
	v_lshlrev_b32_e32 v20, 16, v3
	v_lshl_add_u64 v[0:1], s[16:17], 0, v[20:21]
	v_lshlrev_b64 v[4:5], 2, v[22:23]
	v_lshl_add_u64 v[6:7], v[0:1], 0, v[4:5]
	v_lshl_add_u64 v[4:5], s[16:17], 0, v[4:5]
	v_lshlrev_b32_e32 v0, 2, v14
	v_mov_b32_e32 v1, v21
	v_lshl_add_u64 v[4:5], v[4:5], 0, v[20:21]
	v_lshl_add_u64 v[4:5], v[4:5], 0, v[0:1]
	v_add_co_u32_e32 v4, vcc, 0x200000, v4
	v_lshl_add_u64 v[6:7], v[6:7], 0, v[0:1]
	s_nop 0
	v_addc_co_u32_e32 v5, vcc, 0, v5, vcc
	v_readlane_b32 s36, v250, 19
	global_load_dword v7, v[6:7], off
	v_readlane_b32 s37, v250, 20
	global_load_dword v4, v[4:5], off
	v_lshlrev_b32_e32 v6, 2, v3
	s_mov_b32 s2, 0xbfb8aa3b
	v_readlane_b32 s38, v250, 21
	v_readlane_b32 s39, v250, 22
	global_load_dword v5, v6, s[36:37]
	v_readlane_b32 s40, v250, 23
	v_readlane_b32 s41, v250, 24
	v_readlane_b32 s42, v250, 25
	v_readlane_b32 s43, v250, 26
	v_readlane_b32 s44, v250, 27
	v_readlane_b32 s45, v250, 28
	v_readlane_b32 s46, v250, 29
	v_readlane_b32 s47, v250, 30
	v_readlane_b32 s48, v250, 31
	v_readlane_b32 s49, v250, 32
	v_readlane_b32 s50, v250, 33
	v_readlane_b32 s51, v250, 34
	v_readlane_b32 s36, v250, 3
	v_readlane_b32 s50, v250, 17
	v_readlane_b32 s51, v250, 18
	v_readlane_b32 s4, v250, 41
	v_readlane_b32 s5, v250, 42
	v_readlane_b32 s37, v250, 4
	v_readlane_b32 s38, v250, 5
	v_readlane_b32 s39, v250, 6
	global_load_dword v6, v6, s[50:51]
	v_readlane_b32 s40, v250, 7
	v_readlane_b32 s41, v250, 8
	v_readlane_b32 s42, v250, 9
	v_readlane_b32 s43, v250, 10
	v_readlane_b32 s44, v250, 11
	v_readlane_b32 s45, v250, 12
	v_readlane_b32 s46, v250, 13
	v_readlane_b32 s47, v250, 14
	v_readlane_b32 s48, v250, 15
	v_readlane_b32 s49, v250, 16
	s_waitcnt vmcnt(2)
	v_mul_f32_e32 v4, 0xbfb8aa3b, v4
	v_exp_f32_e32 v4, v4
	s_waitcnt vmcnt(1)
	v_add_f32_e32 v5, v7, v5
	v_mul_f32_e64 v8, |v5|, s2
	v_fma_f32 v9, |v5|, s2, -v8
	s_mov_b32 s2, 0xb2a5705f
	v_rndne_f32_e32 v10, v8
	v_fma_f32 v9, |v5|, s2, v9
	v_sub_f32_e32 v8, v8, v10
	v_add_f32_e32 v8, v8, v9
	v_exp_f32_e32 v8, v8
	v_cvt_i32_f32_e32 v9, v10
	s_mov_b32 s2, 0x42ce8ed0
	v_cmp_ngt_f32_e64 vcc, |v5|, s2
	s_mov_b32 s2, 0xc2b17218
	v_ldexp_f32 v8, v8, v9
	v_cndmask_b32_e32 v8, 0, v8, vcc
	v_cmp_nlt_f32_e64 vcc, |v5|, s2
	v_max_f32_e32 v7, 0, v5
	s_mov_b32 s2, 0x3f2aaaab
	v_cndmask_b32_e32 v5, v193, v8, vcc
	v_add_f32_e32 v10, 1.0, v5
	v_add_f32_e32 v8, -1.0, v10
	v_sub_f32_e32 v9, v8, v10
	v_add_f32_e32 v9, 1.0, v9
	v_sub_f32_e32 v8, v5, v8
	v_add_f32_e32 v11, v8, v9
	v_frexp_mant_f32_e32 v8, v10
	v_cmp_gt_f32_e32 vcc, s2, v8
	v_cvt_f64_f32_e32 v[8:9], v10
	v_frexp_exp_i32_f64_e32 v8, v[8:9]
	v_subbrev_co_u32_e32 v8, vcc, 0, v8, vcc
	v_sub_u32_e32 v9, 0, v8
	v_ldexp_f32 v10, v10, v9
	v_ldexp_f32 v9, v11, v9
	v_add_f32_e32 v11, -1.0, v10
	v_add_f32_e32 v17, 1.0, v11
	v_sub_f32_e32 v17, v10, v17
	v_add_f32_e32 v17, v9, v17
	v_add_f32_e32 v18, v11, v17
	v_sub_f32_e32 v11, v11, v18
	v_add_f32_e32 v11, v17, v11
	v_add_f32_e32 v17, 1.0, v10
	v_add_f32_e32 v19, -1.0, v17
	v_sub_f32_e32 v10, v10, v19
	v_add_f32_e32 v9, v9, v10
	v_add_f32_e32 v10, v17, v9
	v_sub_f32_e32 v17, v17, v10
	v_add_f32_e32 v9, v9, v17
	v_rcp_f32_e32 v17, v10
	v_cvt_f32_i32_e32 v8, v8
	s_mov_b32 s2, 0x3f317218
	v_add_f32_e32 v4, 1.0, v4
	v_mul_f32_e32 v19, v18, v17
	v_mul_f32_e32 v20, v10, v19
	v_fma_f32 v25, v19, v10, -v20
	v_fmac_f32_e32 v25, v19, v9
	v_add_f32_e32 v36, v20, v25
	v_sub_f32_e32 v40, v18, v36
	v_sub_f32_e32 v18, v18, v40
	v_sub_f32_e32 v20, v36, v20
	v_sub_f32_e32 v18, v18, v36
	v_add_f32_e32 v11, v11, v18
	v_sub_f32_e32 v18, v20, v25
	v_add_f32_e32 v11, v18, v11
	v_add_f32_e32 v18, v40, v11
	v_mul_f32_e32 v20, v17, v18
	v_mul_f32_e32 v25, v10, v20
	v_fma_f32 v10, v20, v10, -v25
	v_fmac_f32_e32 v10, v20, v9
	v_sub_f32_e32 v9, v40, v18
	v_add_f32_e32 v9, v11, v9
	v_add_f32_e32 v11, v25, v10
	v_sub_f32_e32 v36, v18, v11
	v_sub_f32_e32 v18, v18, v36
	v_sub_f32_e32 v25, v11, v25
	v_sub_f32_e32 v11, v18, v11
	v_add_f32_e32 v9, v9, v11
	v_sub_f32_e32 v10, v25, v10
	v_add_f32_e32 v9, v10, v9
	v_add_f32_e32 v10, v19, v20
	v_add_f32_e32 v9, v36, v9
	v_sub_f32_e32 v11, v10, v19
	v_mul_f32_e32 v9, v17, v9
	v_sub_f32_e32 v11, v20, v11
	v_add_f32_e32 v9, v11, v9
	v_mul_f32_e32 v19, 0x3f317218, v8
	v_add_f32_e32 v11, v10, v9
	v_fma_f32 v20, v8, s2, -v19
	v_mul_f32_e32 v17, v11, v11
	v_fmac_f32_e32 v20, 0xb102e308, v8
	v_sub_f32_e32 v8, v11, v10
	v_fmamk_f32 v18, v17, 0x3e9b6dac, v188
	v_sub_f32_e32 v8, v9, v8
	v_add_f32_e32 v9, v19, v20
	v_fmaak_f32 v18, v17, v18, 0x3f2aaada
	v_sub_f32_e32 v10, v9, v19
	v_ldexp_f32 v19, v11, 1
	v_mul_f32_e32 v11, v11, v17
	v_mul_f32_e32 v11, v11, v18
	v_add_f32_e32 v17, v19, v11
	v_sub_f32_e32 v18, v17, v19
	v_ldexp_f32 v8, v8, 1
	v_sub_f32_e32 v11, v11, v18
	v_add_f32_e32 v8, v8, v11
	v_add_f32_e32 v11, v17, v8
	v_sub_f32_e32 v17, v11, v17
	v_sub_f32_e32 v8, v8, v17
	v_add_f32_e32 v17, v9, v11
	v_sub_f32_e32 v18, v17, v9
	v_sub_f32_e32 v19, v17, v18
	v_sub_f32_e32 v10, v20, v10
	v_sub_f32_e32 v9, v9, v19
	v_sub_f32_e32 v11, v11, v18
	v_add_f32_e32 v9, v11, v9
	v_add_f32_e32 v11, v10, v8
	v_sub_f32_e32 v18, v11, v10
	v_sub_f32_e32 v19, v11, v18
	v_sub_f32_e32 v10, v10, v19
	v_sub_f32_e32 v8, v8, v18
	v_add_f32_e32 v9, v11, v9
	v_add_f32_e32 v8, v8, v10
	v_add_f32_e32 v10, v17, v9
	v_sub_f32_e32 v11, v10, v17
	v_sub_f32_e32 v9, v9, v11
	v_add_f32_e32 v8, v8, v9
	s_mov_b32 s2, 0x7f800000
	v_add_f32_e32 v8, v10, v8
	v_cmp_neq_f32_e32 vcc, s2, v5
	s_mov_b32 s2, 0x33800000
	v_rcp_f32_e32 v4, v4
	v_cndmask_b32_e32 v8, v193, v8, vcc
	v_cmp_lt_f32_e64 vcc, |v5|, s2
	s_mov_b32 s2, 0x3fb8aa3b
	v_lshlrev_b32_e32 v20, 2, v39
	v_cndmask_b32_e32 v5, v8, v5, vcc
	v_add_f32_e32 v5, v7, v5
	s_waitcnt vmcnt(0)
	v_mul_f32_e32 v7, 0x3fb8aa3b, v6
	v_fma_f32 v8, v6, s2, -v7
	v_rndne_f32_e32 v9, v7
	v_fmac_f32_e32 v8, 0x32a5705f, v6
	v_sub_f32_e32 v7, v7, v9
	v_add_f32_e32 v7, v7, v8
	v_exp_f32_e32 v7, v7
	v_cvt_i32_f32_e32 v8, v9
	s_mov_b32 s2, 0xc2ce8ed0
	v_cmp_ngt_f32_e32 vcc, s2, v6
	s_mov_b32 s2, 0x42b17218
	v_ldexp_f32 v7, v7, v8
	v_cndmask_b32_e32 v7, 0, v7, vcc
	v_cmp_nlt_f32_e32 vcc, s2, v6
	v_add_u32_e32 v8, -1, v191
	s_nop 0
	v_cndmask_b32_e32 v7, v193, v7, vcc
	v_cmp_lt_i32_e32 vcc, v8, v47
	v_mul_f32_e64 v6, v5, -v7
	s_nop 0
	v_cndmask_b32_e32 v8, v8, v191, vcc
	v_lshlrev_b32_e32 v8, 2, v8
	ds_bpermute_b32 v8, v8, v6
	v_cmp_eq_u32_e32 vcc, 0, v14
	s_waitcnt lgkmcnt(0)
	v_fma_f32 v5, v5, -v7, v8
	v_cndmask_b32_e32 v5, v5, v6, vcc
	v_add_u32_e32 v6, -2, v191
	v_cmp_lt_i32_e32 vcc, v6, v47
	s_nop 1
	v_cndmask_b32_e32 v6, v6, v191, vcc
	v_lshlrev_b32_e32 v6, 2, v6
	ds_bpermute_b32 v6, v6, v5
	v_cmp_gt_u32_e32 vcc, 2, v14
	s_waitcnt lgkmcnt(0)
	v_add_f32_e32 v6, v5, v6
	v_cndmask_b32_e32 v5, v6, v5, vcc
	v_add_u32_e32 v6, -4, v191
	v_cmp_lt_i32_e32 vcc, v6, v47
	s_nop 1
	v_cndmask_b32_e32 v6, v6, v191, vcc
	v_lshlrev_b32_e32 v6, 2, v6
	ds_bpermute_b32 v6, v6, v5
	v_cmp_gt_u32_e32 vcc, 4, v14
	s_waitcnt lgkmcnt(0)
	v_add_f32_e32 v6, v5, v6
	v_cndmask_b32_e32 v5, v6, v5, vcc
	v_add_u32_e32 v6, -8, v191
	v_cmp_lt_i32_e32 vcc, v6, v47
	s_nop 1
	v_cndmask_b32_e32 v6, v6, v191, vcc
	v_lshlrev_b32_e32 v6, 2, v6
	ds_bpermute_b32 v6, v6, v5
	v_cmp_gt_u32_e32 vcc, 8, v14
	s_waitcnt lgkmcnt(0)
	v_add_f32_e32 v6, v5, v6
	v_cndmask_b32_e32 v5, v6, v5, vcc
	v_add_u32_e32 v6, -16, v191
	v_cmp_lt_i32_e32 vcc, v6, v47
	s_nop 1
	v_cndmask_b32_e32 v6, v6, v191, vcc
	v_lshlrev_b32_e32 v6, 2, v6
	ds_bpermute_b32 v6, v6, v5
	v_cmp_gt_u32_e32 vcc, 16, v14
	s_waitcnt lgkmcnt(0)
	v_add_f32_e32 v6, v5, v6
	v_cndmask_b32_e32 v5, v6, v5, vcc
	v_subrev_u32_e32 v6, 32, v191
	v_cmp_lt_i32_e32 vcc, v6, v47
	s_nop 1
	v_cndmask_b32_e32 v6, v6, v191, vcc
	v_lshlrev_b32_e32 v6, 2, v6
	ds_bpermute_b32 v6, v6, v5
	v_cmp_gt_u32_e32 vcc, 32, v14
	s_waitcnt lgkmcnt(0)
	v_add_f32_e32 v6, v5, v6
	v_cndmask_b32_e32 v6, v6, v5, vcc
	v_lshlrev_b32_e32 v5, 2, v194
	v_add_u32_e32 v7, v15, v5
	ds_write_b32 v7, v6
	v_add_u32_e32 v7, v13, v5
	ds_write_b32 v7, v4
	v_mul_f32_e32 v7, 0x3fb8aa3b, v6
	v_exp_f32_e32 v7, v7
	v_add_u32_e32 v5, v12, v5
	v_mul_f32_e32 v4, v4, v7
	ds_write_b32 v5, v4
	v_or_b32_e32 v4, v3, v16
	v_ashrrev_i32_e32 v5, 31, v4
	v_lshlrev_b64 v[4:5], 15, v[4:5]
	v_lshl_add_u64 v[4:5], s[4:5], 0, v[4:5]
	v_lshl_add_u64 v[4:5], v[4:5], 0, v[20:21]
	v_lshl_add_u64 v[0:1], v[4:5], 0, v[0:1]
	global_store_dword v[0:1], v6, off
	v_mov_b32_e32 v0, 0x8800

.LBB0_871:
	s_or_b64 exec, exec, s[30:31]
	s_waitcnt lgkmcnt(0)
	s_barrier
	ds_read_b128 v[0:3], v33
	ds_read_b128 v[4:7], v33 offset:1024
	ds_read_b128 v[8:11], v33 offset:2048
	ds_read_b128 v[12:15], v33 offset:3072
	ds_read_b128 v[16:19], v33 offset:4096
	ds_read_b128 v[20:23], v33 offset:5120
	ds_read_b128 v[24:27], v33 offset:6144
	ds_read_b128 v[28:31], v33 offset:7168
	global_load_dwordx4 v[108:111], v[38:39], off
	global_load_dwordx4 v[112:115], v[38:39], off offset:1024
	global_load_dwordx4 v[116:119], v[38:39], off offset:2048
	global_load_dwordx4 v[120:123], v[38:39], off offset:3072
	global_load_dwordx4 v[124:127], v[40:41], off
	global_load_dwordx4 v[128:131], v[42:43], off
	global_load_dwordx4 v[132:135], v[44:45], off
	global_load_dwordx4 v[136:139], v[46:47], off
	s_mov_b32 s12, 0
	s_branch .LBB0_873
.LBB0_873:
	s_nop 0
	v_add_u32_e32 v102, s12, v86
	v_ashrrev_i32_e32 v103, 31, v102
	v_mov_b32_e32 v246, 0
	v_mov_b32_e32 v247, 0
	v_lshlrev_b32_e32 v34, 2, v32
	v_mov_b32_e32 v51, v35
	v_mov_b32_e32 v53, v35
	v_mov_b32_e32 v55, v35
	v_mov_b32_e32 v57, v35
	s_and_saveexec_b64 s[10:11], s[8:9]
	s_cbranch_execz .Lfin_noss
	v_lshlrev_b64 v[92:93], 7, v[102:103]
	v_lshl_add_u64 v[92:93], v[36:37], 0, v[92:93]
	global_load_dword v246, v[92:93], off
	global_load_dword v247, v[92:93], off offset:128
.Lfin_noss:
	s_or_b64 exec, exec, s[10:11]
	v_lshlrev_b64 v[58:59], 12, v[102:103]
	v_lshlrev_b64 v[94:95], 13, v[102:103]
	v_lshl_add_u64 v[58:59], v[48:49], 0, v[58:59]
	v_lshl_add_u64 v[60:61], s[56:57], 0, v[94:95]
	v_lshl_add_u64 v[62:63], s[80:81], 0, v[94:95]
	v_add_co_u32_e32 v66, vcc, 0x1000, v58
	v_lshl_add_u64 v[92:93], v[60:61], 0, v[34:35]
	s_nop 0
	v_addc_co_u32_e32 v67, vcc, 0, v59, vcc
	v_add_co_u32_e32 v88, vcc, 0x2000, v60
	s_nop 1
	v_addc_co_u32_e32 v89, vcc, 0, v61, vcc
	v_add_co_u32_e32 v90, vcc, 0x2000, v62
	s_nop 1
	v_addc_co_u32_e32 v91, vcc, 0, v63, vcc
	v_lshl_add_u64 v[94:95], v[60:61], 0, v[50:51]
	v_lshl_add_u64 v[96:97], v[60:61], 0, v[52:53]
	v_lshl_add_u64 v[98:99], v[60:61], 0, v[54:55]
	v_lshl_add_u64 v[100:101], v[60:61], 0, v[56:57]
	global_load_dwordx2 v[140:141], v[58:59], off
	global_load_dwordx4 v[182:185], v[92:93], off
	global_load_dwordx2 v[142:143], v[58:59], off offset:512
	global_load_dwordx4 v[186:189], v[92:93], off offset:1024
	global_load_dwordx2 v[144:145], v[58:59], off offset:1024
	global_load_dwordx4 v[190:193], v[92:93], off offset:2048
	global_load_dwordx2 v[146:147], v[58:59], off offset:1536
	global_load_dwordx4 v[194:197], v[92:93], off offset:3072
	global_load_dwordx2 v[148:149], v[58:59], off offset:2048
	global_load_dwordx4 v[198:201], v[94:95], off
	global_load_dwordx2 v[150:151], v[58:59], off offset:2560
	global_load_dwordx4 v[202:205], v[96:97], off
	global_load_dwordx2 v[152:153], v[58:59], off offset:3072
	global_load_dwordx4 v[206:209], v[98:99], off
	global_load_dwordx2 v[154:155], v[58:59], off offset:3584
	global_load_dwordx4 v[210:213], v[100:101], off
	v_lshl_add_u64 v[92:93], v[88:89], 0, v[34:35]
	v_lshl_add_u64 v[94:95], v[88:89], 0, v[50:51]
	v_lshl_add_u64 v[96:97], v[88:89], 0, v[52:53]
	v_lshl_add_u64 v[98:99], v[88:89], 0, v[54:55]
	v_lshl_add_u64 v[100:101], v[88:89], 0, v[56:57]
	global_load_dwordx2 v[166:167], v[66:67], off
	global_load_dwordx4 v[214:217], v[92:93], off
	global_load_dwordx2 v[168:169], v[66:67], off offset:512
	global_load_dwordx4 v[218:221], v[92:93], off offset:1024
	global_load_dwordx2 v[170:171], v[66:67], off offset:1024
	global_load_dwordx4 v[222:225], v[92:93], off offset:2048
	global_load_dwordx2 v[172:173], v[66:67], off offset:1536
	global_load_dwordx4 v[226:229], v[92:93], off offset:3072
	global_load_dwordx2 v[174:175], v[66:67], off offset:2048
	global_load_dwordx4 v[230:233], v[94:95], off
	global_load_dwordx2 v[176:177], v[66:67], off offset:2560
	global_load_dwordx4 v[234:237], v[96:97], off
	global_load_dwordx2 v[178:179], v[66:67], off offset:3072
	global_load_dwordx4 v[238:241], v[98:99], off
	global_load_dwordx2 v[180:181], v[66:67], off offset:3584
	global_load_dwordx4 v[242:245], v[100:101], off
	s_waitcnt vmcnt(32)
	ds_bpermute_b32 v248, v65, v246
	ds_bpermute_b32 v249, v65, v247
	s_waitcnt lgkmcnt(0)
	v_add_f32_e32 v246, v246, v248
	v_add_f32_e32 v247, v247, v249
	ds_bpermute_b32 v248, v68, v246
	ds_bpermute_b32 v249, v68, v247
	s_waitcnt lgkmcnt(0)
	v_add_f32_e32 v246, v246, v248
	v_add_f32_e32 v247, v247, v249
	ds_bpermute_b32 v248, v69, v246
	ds_bpermute_b32 v249, v69, v247
	s_waitcnt lgkmcnt(0)
	v_add_f32_e32 v246, v246, v248
	v_add_f32_e32 v247, v247, v249
	ds_bpermute_b32 v248, v70, v246
	ds_bpermute_b32 v249, v70, v247
	s_waitcnt lgkmcnt(0)
	v_add_f32_e32 v246, v246, v248
	v_add_f32_e32 v247, v247, v249
	ds_bpermute_b32 v248, v71, v246
	ds_bpermute_b32 v249, v71, v247
	s_waitcnt lgkmcnt(0)
	v_add_f32_e32 v246, v246, v248
	v_add_f32_e32 v247, v247, v249
	ds_bpermute_b32 v248, v72, v246
	ds_bpermute_b32 v249, v72, v247
	s_waitcnt lgkmcnt(0)
	v_add_f32_e32 v246, v246, v248
	v_add_f32_e32 v247, v247, v249
	v_fmamk_f32 v246, v246, 0x3a000000, v87
	v_fmamk_f32 v247, v247, 0x3a000000, v87
	v_mul_f32_e32 v248, 0x4b800000, v246
	v_cmp_gt_f32_e32 vcc, s33, v246
	v_mul_f32_e32 v249, 0x4b800000, v247
	v_cmp_gt_f32_e64 s[10:11], s33, v247
	s_nop 0
	v_cndmask_b32_e32 v246, v246, v248, vcc
	v_cndmask_b32_e64 v247, v247, v249, s[10:11]
	v_rsq_f32_e32 v246, v246
	v_rsq_f32_e32 v247, v247
	s_nop 0
	v_mul_f32_e32 v248, 0x45800000, v246
	v_mul_f32_e32 v249, 0x45800000, v247
	v_cndmask_b32_e32 v104, v246, v248, vcc
	v_cndmask_b32_e64 v106, v247, v249, s[10:11]
	v_lshl_add_u64 v[98:99], v[62:63], 0, v[34:35]
	v_lshl_add_u64 v[100:101], v[90:91], 0, v[34:35]
	s_waitcnt vmcnt(30)
	v_lshlrev_b32_e32 v156, 16, v140
	v_and_b32_e32 v157, 0xffff0000, v140
	v_lshlrev_b32_e32 v158, 16, v141
	v_and_b32_e32 v159, 0xffff0000, v141
	v_pk_mul_f32 v[156:157], v[104:105], v[156:157] op_sel_hi:[0,1]
	v_pk_mul_f32 v[158:159], v[104:105], v[158:159] op_sel_hi:[0,1]
	v_pk_mul_f32 v[156:157], v[108:109], v[156:157]
	v_pk_mul_f32 v[158:159], v[110:111], v[158:159]
	v_pk_fma_f32 v[182:183], v[0:1], v[156:157], v[182:183]
	v_pk_fma_f32 v[184:185], v[2:3], v[158:159], v[184:185]
	global_store_dwordx4 v[98:99], v[182:185], off
	s_waitcnt vmcnt(29)
	v_lshlrev_b32_e32 v160, 16, v142
	v_and_b32_e32 v161, 0xffff0000, v142
	v_lshlrev_b32_e32 v162, 16, v143
	v_and_b32_e32 v163, 0xffff0000, v143
	v_pk_mul_f32 v[160:161], v[104:105], v[160:161] op_sel_hi:[0,1]
	v_pk_mul_f32 v[162:163], v[104:105], v[162:163] op_sel_hi:[0,1]
	v_pk_mul_f32 v[160:161], v[112:113], v[160:161]
	v_pk_mul_f32 v[162:163], v[114:115], v[162:163]
	v_pk_fma_f32 v[186:187], v[4:5], v[160:161], v[186:187]
	v_pk_fma_f32 v[188:189], v[6:7], v[162:163], v[188:189]
	global_store_dwordx4 v[98:99], v[186:189], off offset:1024
	s_waitcnt vmcnt(28)
	v_lshlrev_b32_e32 v156, 16, v144
	v_and_b32_e32 v157, 0xffff0000, v144
	v_lshlrev_b32_e32 v158, 16, v145
	v_and_b32_e32 v159, 0xffff0000, v145
	v_pk_mul_f32 v[156:157], v[104:105], v[156:157] op_sel_hi:[0,1]
	v_pk_mul_f32 v[158:159], v[104:105], v[158:159] op_sel_hi:[0,1]
	v_pk_mul_f32 v[156:157], v[116:117], v[156:157]
	v_pk_mul_f32 v[158:159], v[118:119], v[158:159]
	v_pk_fma_f32 v[190:191], v[8:9], v[156:157], v[190:191]
	v_pk_fma_f32 v[192:193], v[10:11], v[158:159], v[192:193]
	global_store_dwordx4 v[98:99], v[190:193], off offset:2048
	s_waitcnt vmcnt(27)
	v_lshlrev_b32_e32 v160, 16, v146
	v_and_b32_e32 v161, 0xffff0000, v146
	v_lshlrev_b32_e32 v162, 16, v147
	v_and_b32_e32 v163, 0xffff0000, v147
	v_pk_mul_f32 v[160:161], v[104:105], v[160:161] op_sel_hi:[0,1]
	v_pk_mul_f32 v[162:163], v[104:105], v[162:163] op_sel_hi:[0,1]
	v_pk_mul_f32 v[160:161], v[120:121], v[160:161]
	v_pk_mul_f32 v[162:163], v[122:123], v[162:163]
	v_pk_fma_f32 v[194:195], v[12:13], v[160:161], v[194:195]
	v_pk_fma_f32 v[196:197], v[14:15], v[162:163], v[196:197]
	global_store_dwordx4 v[98:99], v[194:197], off offset:3072
	s_waitcnt vmcnt(26)
	v_lshlrev_b32_e32 v156, 16, v148
	v_and_b32_e32 v157, 0xffff0000, v148
	v_lshlrev_b32_e32 v158, 16, v149
	v_and_b32_e32 v159, 0xffff0000, v149
	v_pk_mul_f32 v[156:157], v[104:105], v[156:157] op_sel_hi:[0,1]
	v_pk_mul_f32 v[158:159], v[104:105], v[158:159] op_sel_hi:[0,1]
	v_lshl_add_u64 v[94:95], v[62:63], 0, v[50:51]
	v_pk_mul_f32 v[156:157], v[124:125], v[156:157]
	v_pk_mul_f32 v[158:159], v[126:127], v[158:159]
	v_pk_fma_f32 v[198:199], v[16:17], v[156:157], v[198:199]
	v_pk_fma_f32 v[200:201], v[18:19], v[158:159], v[200:201]
	global_store_dwordx4 v[94:95], v[198:201], off
	s_waitcnt vmcnt(25)
	v_lshlrev_b32_e32 v160, 16, v150
	v_and_b32_e32 v161, 0xffff0000, v150
	v_lshlrev_b32_e32 v162, 16, v151
	v_and_b32_e32 v163, 0xffff0000, v151
	v_pk_mul_f32 v[160:161], v[104:105], v[160:161] op_sel_hi:[0,1]
	v_pk_mul_f32 v[162:163], v[104:105], v[162:163] op_sel_hi:[0,1]
	v_lshl_add_u64 v[96:97], v[62:63], 0, v[52:53]
	v_pk_mul_f32 v[160:161], v[128:129], v[160:161]
	v_pk_mul_f32 v[162:163], v[130:131], v[162:163]
	v_pk_fma_f32 v[202:203], v[20:21], v[160:161], v[202:203]
	v_pk_fma_f32 v[204:205], v[22:23], v[162:163], v[204:205]
	global_store_dwordx4 v[96:97], v[202:205], off
	s_waitcnt vmcnt(24)
	v_lshlrev_b32_e32 v156, 16, v152
	v_and_b32_e32 v157, 0xffff0000, v152
	v_lshlrev_b32_e32 v158, 16, v153
	v_and_b32_e32 v159, 0xffff0000, v153
	v_pk_mul_f32 v[156:157], v[104:105], v[156:157] op_sel_hi:[0,1]
	v_pk_mul_f32 v[158:159], v[104:105], v[158:159] op_sel_hi:[0,1]
	v_lshl_add_u64 v[94:95], v[62:63], 0, v[54:55]
	v_pk_mul_f32 v[156:157], v[132:133], v[156:157]
	v_pk_mul_f32 v[158:159], v[134:135], v[158:159]
	v_pk_fma_f32 v[206:207], v[24:25], v[156:157], v[206:207]
	v_pk_fma_f32 v[208:209], v[26:27], v[158:159], v[208:209]
	global_store_dwordx4 v[94:95], v[206:209], off
	s_waitcnt vmcnt(23)
	v_lshlrev_b32_e32 v160, 16, v154
	v_and_b32_e32 v161, 0xffff0000, v154
	v_lshlrev_b32_e32 v162, 16, v155
	v_and_b32_e32 v163, 0xffff0000, v155
	v_pk_mul_f32 v[160:161], v[104:105], v[160:161] op_sel_hi:[0,1]
	v_pk_mul_f32 v[162:163], v[104:105], v[162:163] op_sel_hi:[0,1]
	v_lshl_add_u64 v[96:97], v[62:63], 0, v[56:57]
	v_pk_mul_f32 v[160:161], v[136:137], v[160:161]
	v_pk_mul_f32 v[162:163], v[138:139], v[162:163]
	v_pk_fma_f32 v[210:211], v[28:29], v[160:161], v[210:211]
	v_pk_fma_f32 v[212:213], v[30:31], v[162:163], v[212:213]
	global_store_dwordx4 v[96:97], v[210:213], off
	s_waitcnt vmcnt(22)
	v_lshlrev_b32_e32 v156, 16, v166
	v_and_b32_e32 v157, 0xffff0000, v166
	v_lshlrev_b32_e32 v158, 16, v167
	v_and_b32_e32 v159, 0xffff0000, v167
	v_pk_mul_f32 v[156:157], v[106:107], v[156:157] op_sel_hi:[0,1]
	v_pk_mul_f32 v[158:159], v[106:107], v[158:159] op_sel_hi:[0,1]
	v_pk_mul_f32 v[156:157], v[108:109], v[156:157]
	v_pk_mul_f32 v[158:159], v[110:111], v[158:159]
	v_pk_fma_f32 v[214:215], v[0:1], v[156:157], v[214:215]
	v_pk_fma_f32 v[216:217], v[2:3], v[158:159], v[216:217]
	global_store_dwordx4 v[100:101], v[214:217], off
	s_waitcnt vmcnt(21)
	v_lshlrev_b32_e32 v160, 16, v168
	v_and_b32_e32 v161, 0xffff0000, v168
	v_lshlrev_b32_e32 v162, 16, v169
	v_and_b32_e32 v163, 0xffff0000, v169
	v_pk_mul_f32 v[160:161], v[106:107], v[160:161] op_sel_hi:[0,1]
	v_pk_mul_f32 v[162:163], v[106:107], v[162:163] op_sel_hi:[0,1]
	v_pk_mul_f32 v[160:161], v[112:113], v[160:161]
	v_pk_mul_f32 v[162:163], v[114:115], v[162:163]
	v_pk_fma_f32 v[218:219], v[4:5], v[160:161], v[218:219]
	v_pk_fma_f32 v[220:221], v[6:7], v[162:163], v[220:221]
	global_store_dwordx4 v[100:101], v[218:221], off offset:1024
	s_waitcnt vmcnt(20)
	v_lshlrev_b32_e32 v156, 16, v170
	v_and_b32_e32 v157, 0xffff0000, v170
	v_lshlrev_b32_e32 v158, 16, v171
	v_and_b32_e32 v159, 0xffff0000, v171
	v_pk_mul_f32 v[156:157], v[106:107], v[156:157] op_sel_hi:[0,1]
	v_pk_mul_f32 v[158:159], v[106:107], v[158:159] op_sel_hi:[0,1]
	v_pk_mul_f32 v[156:157], v[116:117], v[156:157]
	v_pk_mul_f32 v[158:159], v[118:119], v[158:159]
	v_pk_fma_f32 v[222:223], v[8:9], v[156:157], v[222:223]
	v_pk_fma_f32 v[224:225], v[10:11], v[158:159], v[224:225]
	global_store_dwordx4 v[100:101], v[222:225], off offset:2048
	s_waitcnt vmcnt(19)
	v_lshlrev_b32_e32 v160, 16, v172
	v_and_b32_e32 v161, 0xffff0000, v172
	v_lshlrev_b32_e32 v162, 16, v173
	v_and_b32_e32 v163, 0xffff0000, v173
	v_pk_mul_f32 v[160:161], v[106:107], v[160:161] op_sel_hi:[0,1]
	v_pk_mul_f32 v[162:163], v[106:107], v[162:163] op_sel_hi:[0,1]
	v_pk_mul_f32 v[160:161], v[120:121], v[160:161]
	v_pk_mul_f32 v[162:163], v[122:123], v[162:163]
	v_pk_fma_f32 v[226:227], v[12:13], v[160:161], v[226:227]
	v_pk_fma_f32 v[228:229], v[14:15], v[162:163], v[228:229]
	global_store_dwordx4 v[100:101], v[226:229], off offset:3072
	s_waitcnt vmcnt(18)
	v_lshlrev_b32_e32 v156, 16, v174
	v_and_b32_e32 v157, 0xffff0000, v174
	v_lshlrev_b32_e32 v158, 16, v175
	v_and_b32_e32 v159, 0xffff0000, v175
	v_pk_mul_f32 v[156:157], v[106:107], v[156:157] op_sel_hi:[0,1]
	v_pk_mul_f32 v[158:159], v[106:107], v[158:159] op_sel_hi:[0,1]
	v_lshl_add_u64 v[94:95], v[90:91], 0, v[50:51]
	v_pk_mul_f32 v[156:157], v[124:125], v[156:157]
	v_pk_mul_f32 v[158:159], v[126:127], v[158:159]
	v_pk_fma_f32 v[230:231], v[16:17], v[156:157], v[230:231]
	v_pk_fma_f32 v[232:233], v[18:19], v[158:159], v[232:233]
	global_store_dwordx4 v[94:95], v[230:233], off
	s_waitcnt vmcnt(17)
	v_lshlrev_b32_e32 v160, 16, v176
	v_and_b32_e32 v161, 0xffff0000, v176
	v_lshlrev_b32_e32 v162, 16, v177
	v_and_b32_e32 v163, 0xffff0000, v177
	v_pk_mul_f32 v[160:161], v[106:107], v[160:161] op_sel_hi:[0,1]
	v_pk_mul_f32 v[162:163], v[106:107], v[162:163] op_sel_hi:[0,1]
	v_lshl_add_u64 v[96:97], v[90:91], 0, v[52:53]
	v_pk_mul_f32 v[160:161], v[128:129], v[160:161]
	v_pk_mul_f32 v[162:163], v[130:131], v[162:163]
	v_pk_fma_f32 v[234:235], v[20:21], v[160:161], v[234:235]
	v_pk_fma_f32 v[236:237], v[22:23], v[162:163], v[236:237]
	global_store_dwordx4 v[96:97], v[234:237], off
	s_waitcnt vmcnt(16)
	v_lshlrev_b32_e32 v156, 16, v178
	v_and_b32_e32 v157, 0xffff0000, v178
	v_lshlrev_b32_e32 v158, 16, v179
	v_and_b32_e32 v159, 0xffff0000, v179
	v_pk_mul_f32 v[156:157], v[106:107], v[156:157] op_sel_hi:[0,1]
	v_pk_mul_f32 v[158:159], v[106:107], v[158:159] op_sel_hi:[0,1]
	v_lshl_add_u64 v[94:95], v[90:91], 0, v[54:55]
	v_pk_mul_f32 v[156:157], v[132:133], v[156:157]
	v_pk_mul_f32 v[158:159], v[134:135], v[158:159]
	v_pk_fma_f32 v[238:239], v[24:25], v[156:157], v[238:239]
	v_pk_fma_f32 v[240:241], v[26:27], v[158:159], v[240:241]
	global_store_dwordx4 v[94:95], v[238:241], off
	s_waitcnt vmcnt(15)
	v_lshlrev_b32_e32 v160, 16, v180
	v_and_b32_e32 v161, 0xffff0000, v180
	v_lshlrev_b32_e32 v162, 16, v181
	v_and_b32_e32 v163, 0xffff0000, v181
	v_pk_mul_f32 v[160:161], v[106:107], v[160:161] op_sel_hi:[0,1]
	v_pk_mul_f32 v[162:163], v[106:107], v[162:163] op_sel_hi:[0,1]
	v_lshl_add_u64 v[96:97], v[90:91], 0, v[56:57]
	v_pk_mul_f32 v[160:161], v[136:137], v[160:161]
	v_pk_mul_f32 v[162:163], v[138:139], v[162:163]
	v_pk_fma_f32 v[242:243], v[28:29], v[160:161], v[242:243]
	v_pk_fma_f32 v[244:245], v[30:31], v[162:163], v[244:245]
	global_store_dwordx4 v[96:97], v[242:245], off
	s_add_i32 s12, s12, 2
	s_cmp_eq_u32 s12, 8
	s_cbranch_scc0 .LBB0_873
	s_branch .LBB0_858
